# FFT butterflies: w*d as pk_mul + ONE pk_fma with per-lane negate instead of two pk_fma + v_mov (264 sites), dependent s_nop dropped
# speedup vs baseline: 1.0065x; 1.0065x over previous
.LBB0_643:
	v_and_b32_e32 v79, 0x3ff, v25
	v_and_or_b32 v22, v0, s38, v79
	v_or_b32_e32 v23, 0x2000, v22
	v_ashrrev_i32_e32 v30, 5, v23
	v_lshlrev_b32_e32 v23, 3, v23
	v_lshlrev_b32_e32 v30, 3, v30
	v_add3_u32 v74, 0, v23, v30
	v_or_b32_e32 v23, 0x2400, v22
	v_ashrrev_i32_e32 v30, 5, v23
	v_lshlrev_b32_e32 v23, 3, v23
	v_lshlrev_b32_e32 v30, 3, v30
	v_add3_u32 v75, 0, v23, v30
	v_or_b32_e32 v23, 0x2800, v22
	v_ashrrev_i32_e32 v2, 5, v22
	v_lshl_add_u32 v3, v22, 3, 0
	v_ashrrev_i32_e32 v32, 5, v23
	v_lshl_add_u32 v66, v2, 3, v3
	v_or_b32_e32 v2, 0x400, v22
	v_lshlrev_b32_e32 v23, 3, v23
	v_lshlrev_b32_e32 v32, 3, v32
	v_ashrrev_i32_e32 v2, 5, v2
	v_add3_u32 v76, 0, v23, v32
	v_or_b32_e32 v23, 0x2c00, v22
	v_lshl_add_u32 v67, v2, 3, v3
	v_or_b32_e32 v2, 0x800, v22
	v_ashrrev_i32_e32 v32, 5, v23
	v_ashrrev_i32_e32 v2, 5, v2
	v_lshlrev_b32_e32 v23, 3, v23
	v_lshlrev_b32_e32 v32, 3, v32
	v_lshl_add_u32 v68, v2, 3, v3
	v_or_b32_e32 v2, 0xc00, v22
	v_add3_u32 v77, 0, v23, v32
	v_or_b32_e32 v23, 0x3000, v22
	v_ashrrev_i32_e32 v2, 5, v2
	v_ashrrev_i32_e32 v32, 5, v23
	v_lshl_add_u32 v69, v2, 3, v3
	v_or_b32_e32 v2, 0x1000, v22
	v_lshlrev_b32_e32 v23, 3, v23
	v_lshlrev_b32_e32 v32, 3, v32
	v_ashrrev_i32_e32 v2, 5, v2
	v_add3_u32 v78, 0, v23, v32
	v_or_b32_e32 v23, 0x3400, v22
	v_lshl_add_u32 v70, v2, 3, v3
	v_or_b32_e32 v2, 0x1400, v22
	v_ashrrev_i32_e32 v32, 5, v23
	v_ashrrev_i32_e32 v2, 5, v2
	v_lshlrev_b32_e32 v23, 3, v23
	v_lshlrev_b32_e32 v32, 3, v32
	v_lshl_add_u32 v71, v2, 3, v3
	v_or_b32_e32 v2, 0x1800, v22
	v_add3_u32 v80, 0, v23, v32
	v_or_b32_e32 v23, 0x3800, v22
	v_ashrrev_i32_e32 v2, 5, v2
	v_ashrrev_i32_e32 v32, 5, v23
	v_lshl_add_u32 v72, v2, 3, v3
	v_or_b32_e32 v2, 0x1c00, v22
	v_lshlrev_b32_e32 v23, 3, v23
	v_lshlrev_b32_e32 v32, 3, v32
	v_or_b32_e32 v22, 0x3c00, v22
	v_add3_u32 v81, 0, v23, v32
	v_ashrrev_i32_e32 v23, 5, v22
	v_lshlrev_b32_e32 v22, 3, v22
	v_lshlrev_b32_e32 v23, 3, v23
	v_add3_u32 v82, 0, v22, v23
	v_cvt_f32_u32_e32 v22, v79
	v_ashrrev_i32_e32 v2, 5, v2
	v_lshl_add_u32 v73, v2, 3, v3
	ds_read_b64 v[20:21], v67 offset:8192
	ds_read_b64 v[42:43], v68 offset:16384
	ds_read_b64 v[52:53], v69 offset:24576
	ds_read_b64 v[50:51], v70 offset:32768
	v_mul_f32_e32 v22, 0x38800000, v22
	ds_read_b64 v[46:47], v71 offset:40960
	ds_read_b64 v[48:49], v72 offset:49152
	ds_read_b64 v[2:3], v73 offset:57344
	ds_read_b64 v[30:31], v75
	ds_read_b64 v[44:45], v76
	ds_read_b64 v[60:61], v77
	ds_read_b64 v[56:57], v78
	ds_read_b64 v[54:55], v80
	ds_read_b64 v[58:59], v81
	s_waitcnt vmcnt(0)
	ds_read_b64 v[36:37], v82
	v_cos_f32_e32 v38, v22
	v_sin_f32_e32 v62, v22
	ds_read_b64 v[22:23], v74
	ds_read_b64 v[32:33], v66
	s_mov_b32 s27, s14
	s_waitcnt lgkmcnt(6)
	v_pk_add_f32 v[116:117], v[52:53], v[60:61]
	v_pk_add_f32 v[52:53], v[52:53], v[60:61] neg_lo:[0,1] neg_hi:[0,1]
	s_mov_b32 s81, s15
	s_waitcnt lgkmcnt(0)
	v_pk_add_f32 v[34:35], v[22:23], v[32:33]
	v_pk_add_f32 v[32:33], v[32:33], v[22:23] neg_lo:[0,1] neg_hi:[0,1]
	v_cmp_lt_i32_e32 vcc, s35, v25
	v_pk_mul_f32 v[40:41], v[62:63], v[32:33] op_sel:[0,1] op_sel_hi:[0,0]
	v_mov_b32_e32 v63, v38
	v_pk_fma_f32 v[22:23], v[38:39], v[32:33], v[40:41] op_sel_hi:[0,1,1] neg_hi:[0,0,1]
	v_pk_mul_f32 v[64:65], v[62:63], s[94:95] op_sel_hi:[1,0]
	v_pk_add_f32 v[32:33], v[20:21], v[30:31]
	v_pk_add_f32 v[40:41], v[20:21], v[30:31] neg_lo:[0,1] neg_hi:[0,1]
	v_fma_f32 v20, v62, s88, -v65
	v_pk_add_f32 v[30:31], v[42:43], v[44:45]
	v_pk_add_f32 v[42:43], v[42:43], v[44:45] neg_lo:[0,1] neg_hi:[0,1]
	v_pk_add_f32 v[114:115], v[64:65], v[64:65] op_sel:[1,0] op_sel_hi:[1,0] neg_lo:[0,1] neg_hi:[0,1]
	v_pk_mul_f32 v[44:45], v[20:21], v[42:43] op_sel:[0,1] op_sel_hi:[0,0]
	v_pk_fma_f32 v[20:21], v[114:115], v[42:43], v[44:45] neg_lo:[0,0,1]
	v_pk_mul_f32 v[114:115], v[62:63], s[26:27]
	v_pk_mul_f32 v[42:43], v[62:63], s[14:15]
	v_pk_add_f32 v[60:61], v[114:115], v[114:115] op_sel:[0,1] op_sel_hi:[0,1] neg_lo:[0,1] neg_hi:[0,1]
	v_pk_mul_f32 v[60:61], v[60:61], v[52:53] op_sel:[0,1] op_sel_hi:[1,0]
	v_pk_add_f32 v[118:119], v[42:43], v[42:43] op_sel:[1,0] op_sel_hi:[1,0] neg_lo:[0,1] neg_hi:[0,1]
	v_mov_b32_e32 v39, v62
	v_pk_fma_f32 v[120:121], v[118:119], v[52:53], v[60:61] neg_lo:[0,0,1] neg_hi:[0,0,1]
	v_pk_fma_f32 v[52:53], v[118:119], v[52:53], v[60:61]
	v_fma_f32 v60, v62, s39, -v38
	v_pk_add_f32 v[118:119], v[50:51], v[56:57]
	v_pk_add_f32 v[50:51], v[50:51], v[56:57] neg_lo:[0,1] neg_hi:[0,1]
	v_fma_f32 v52, v38, 0, -v62
	v_pk_mul_f32 v[56:57], v[60:61], v[50:51] op_sel:[0,1] op_sel_hi:[0,0]
	v_pk_fma_f32 v[60:61], v[52:53], v[50:51], v[56:57] neg_lo:[0,0,1] neg_hi:[0,0,1]
	v_pk_fma_f32 v[50:51], v[52:53], v[50:51], v[56:57] op_sel_hi:[0,1,1]
	v_pk_add_f32 v[56:57], v[48:49], v[58:59]
	v_pk_add_f32 v[48:49], v[48:49], v[58:59] neg_lo:[0,1] neg_hi:[0,1]
	v_pk_add_f32 v[58:59], v[64:65], v[64:65] op_sel:[0,1] op_sel_hi:[0,1] neg_lo:[0,1] neg_hi:[0,1]
	v_mov_b32_e32 v121, v53
	v_pk_add_f32 v[52:53], v[46:47], v[54:55]
	v_pk_add_f32 v[46:47], v[46:47], v[54:55] neg_lo:[0,1] neg_hi:[0,1]
	v_fma_f32 v54, v38, s88, -v64
	v_pk_mul_f32 v[58:59], v[58:59], v[48:49] op_sel:[0,1] op_sel_hi:[1,0]
	v_fma_f32 v44, v62, s80, -v43
	v_fma_f32 v50, v38, s26, -v42
	v_pk_fma_f32 v[64:65], v[54:55], v[48:49], v[58:59] neg_lo:[0,0,1] neg_hi:[0,0,1]
	v_pk_fma_f32 v[48:49], v[54:55], v[48:49], v[58:59] op_sel_hi:[0,1,1]
	v_pk_mul_f32 v[38:39], v[38:39], s[80:81]
	v_pk_mul_f32 v[44:45], v[44:45], v[40:41] op_sel:[0,1] op_sel_hi:[0,0]
	v_sub_f32_e32 v48, v115, v39
	v_pk_fma_f32 v[54:55], v[48:49], v[40:41], v[44:45] op_sel_hi:[0,1,1] neg_lo:[0,0,1] neg_hi:[0,0,1]
	v_pk_fma_f32 v[40:41], v[48:49], v[40:41], v[44:45] op_sel_hi:[0,1,1]
	v_sub_f32_e32 v40, v39, v115
	v_mov_b32_e32 v55, v41
	v_pk_mul_f32 v[40:41], v[40:41], v[46:47] op_sel:[0,1] op_sel_hi:[0,0]
	v_pk_fma_f32 v[44:45], v[50:51], v[46:47], v[40:41] op_sel_hi:[0,1,1] neg_lo:[0,0,1]
	v_pk_add_f32 v[40:41], v[2:3], v[36:37]
	v_pk_add_f32 v[2:3], v[2:3], v[36:37] neg_lo:[0,1] neg_hi:[0,1]
	v_pk_add_f32 v[36:37], v[42:43], v[42:43] op_sel:[0,1] op_sel_hi:[0,1] neg_lo:[0,1] neg_hi:[0,1]
	v_pk_mul_f32 v[36:37], v[36:37], v[2:3] op_sel:[0,1] op_sel_hi:[1,0]
	v_pk_add_f32 v[38:39], v[38:39], v[38:39] op_sel:[0,1] op_sel_hi:[0,1] neg_lo:[0,1] neg_hi:[0,1]
	v_pk_fma_f32 v[42:43], v[38:39], v[2:3], v[36:37] neg_lo:[0,0,1] neg_hi:[0,0,1]
	v_pk_fma_f32 v[2:3], v[38:39], v[2:3], v[36:37]
	v_pk_add_f32 v[38:39], v[118:119], v[34:35]
	v_lshlrev_b32_e32 v2, 1, v79
	v_cvt_f32_u32_e32 v2, v2
	v_mov_b32_e32 v43, v3
	v_pk_add_f32 v[34:35], v[34:35], v[118:119] neg_lo:[0,1] neg_hi:[0,1]
	v_mov_b32_e32 v65, v49
	v_mul_f32_e32 v3, 0x38800000, v2
	v_sin_f32_e32 v36, v3
	v_cos_f32_e32 v2, v3
	v_mov_b32_e32 v61, v51
	v_pk_add_f32 v[50:51], v[32:33], v[52:53]
	v_pk_mul_f32 v[46:47], v[36:37], v[34:35] op_sel_hi:[0,1]
	v_pk_fma_f32 v[48:49], v[2:3], v[34:35], v[46:47] op_sel:[0,0,1] op_sel_hi:[0,1,0] neg_hi:[0,0,1]
	v_mov_b32_e32 v37, v2
	v_pk_mul_f32 v[34:35], v[36:37], s[94:95] op_sel_hi:[1,0]
	v_pk_add_f32 v[32:33], v[32:33], v[52:53] neg_lo:[0,1] neg_hi:[0,1]
	v_fma_f32 v46, v36, s88, -v35
	v_pk_mul_f32 v[52:53], v[46:47], v[32:33] op_sel_hi:[0,1]
	v_pk_add_f32 v[58:59], v[34:35], v[34:35] op_sel:[1,0] op_sel_hi:[1,0] neg_lo:[0,1] neg_hi:[0,1]
	v_pk_add_f32 v[114:115], v[30:31], v[56:57]
	v_pk_fma_f32 v[62:63], v[58:59], v[32:33], v[52:53] op_sel:[0,0,1] op_sel_hi:[1,1,0] neg_lo:[0,0,1] neg_hi:[0,0,1]
	v_pk_fma_f32 v[32:33], v[58:59], v[32:33], v[52:53] op_sel:[0,0,1] op_sel_hi:[1,1,0]
	v_fma_f32 v52, v36, s39, -v2
	v_pk_add_f32 v[30:31], v[30:31], v[56:57] neg_lo:[0,1] neg_hi:[0,1]
	v_fma_f32 v32, v2, 0, -v36
	v_pk_mul_f32 v[56:57], v[52:53], v[30:31] op_sel_hi:[0,1]
	v_pk_fma_f32 v[118:119], v[32:33], v[30:31], v[56:57] op_sel:[0,0,1] op_sel_hi:[1,1,0] neg_lo:[0,0,1] neg_hi:[0,0,1]
	v_pk_fma_f32 v[30:31], v[32:33], v[30:31], v[56:57] op_sel:[0,0,1] op_sel_hi:[0,1,0]
	v_fma_f32 v30, v2, s88, -v34
	v_pk_add_f32 v[56:57], v[116:117], v[40:41]
	v_pk_add_f32 v[40:41], v[116:117], v[40:41] neg_lo:[0,1] neg_hi:[0,1]
	v_pk_add_f32 v[34:35], v[34:35], v[34:35] op_sel:[0,1] op_sel_hi:[0,1] neg_lo:[0,1] neg_hi:[0,1]
	v_pk_mul_f32 v[116:117], v[34:35], v[40:41]
	v_mov_b32_e32 v63, v33
	v_pk_fma_f32 v[122:123], v[30:31], v[40:41], v[116:117] op_sel:[0,0,1] op_sel_hi:[0,1,0] neg_lo:[0,0,1]
	v_pk_add_f32 v[40:41], v[60:61], v[22:23]
	v_pk_add_f32 v[22:23], v[22:23], v[60:61] neg_lo:[0,1] neg_hi:[0,1]
	v_mov_b32_e32 v119, v31
	v_pk_mul_f32 v[36:37], v[36:37], v[22:23] op_sel_hi:[0,1]
	v_pk_fma_f32 v[60:61], v[2:3], v[22:23], v[36:37] op_sel:[0,0,1] op_sel_hi:[0,1,0] neg_hi:[0,0,1]
	v_pk_add_f32 v[22:23], v[54:55], v[44:45] neg_lo:[0,1] neg_hi:[0,1]
	v_pk_mul_f32 v[36:37], v[46:47], v[22:23] op_sel_hi:[0,1]
	v_pk_add_f32 v[2:3], v[54:55], v[44:45]
	v_pk_fma_f32 v[44:45], v[58:59], v[22:23], v[36:37] op_sel:[0,0,1] op_sel_hi:[1,1,0] neg_lo:[0,0,1]
	v_pk_add_f32 v[54:55], v[50:51], v[56:57]
	v_pk_add_f32 v[22:23], v[20:21], v[64:65]
	v_pk_add_f32 v[20:21], v[20:21], v[64:65] neg_lo:[0,1] neg_hi:[0,1]
	v_pk_add_f32 v[50:51], v[50:51], v[56:57] neg_lo:[0,1] neg_hi:[0,1]
	v_pk_mul_f32 v[36:37], v[52:53], v[20:21] op_sel_hi:[0,1]
	v_pk_fma_f32 v[46:47], v[32:33], v[20:21], v[36:37] op_sel:[0,0,1] op_sel_hi:[0,1,0] neg_lo:[0,0,1]
	v_pk_add_f32 v[32:33], v[120:121], v[42:43] neg_lo:[0,1] neg_hi:[0,1]
	v_pk_mul_f32 v[34:35], v[34:35], v[32:33]
	v_pk_add_f32 v[20:21], v[120:121], v[42:43]
	v_pk_fma_f32 v[36:37], v[30:31], v[32:33], v[34:35] op_sel:[0,0,1] op_sel_hi:[1,1,0] neg_lo:[0,0,1] neg_hi:[0,0,1]
	v_pk_fma_f32 v[30:31], v[30:31], v[32:33], v[34:35] op_sel:[0,0,1] op_sel_hi:[0,1,0]
	v_lshlrev_b32_e32 v30, 2, v79
	v_cvt_f32_u32_e32 v30, v30
	v_mov_b32_e32 v37, v31
	v_pk_add_f32 v[34:35], v[114:115], v[38:39]
	v_pk_add_f32 v[38:39], v[38:39], v[114:115] neg_lo:[0,1] neg_hi:[0,1]
	v_mul_f32_e32 v31, 0x38800000, v30
	v_sin_f32_e32 v32, v31
	v_cos_f32_e32 v30, v31
	v_add_u32_e32 v0, 0x2000, v0
	s_or_b64 s[10:11], vcc, s[10:11]
	v_pk_mul_f32 v[42:43], v[32:33], v[38:39] op_sel_hi:[0,1]
	v_pk_fma_f32 v[52:53], v[30:31], v[38:39], v[42:43] op_sel:[0,0,1] op_sel_hi:[1,1,0]
	v_pk_fma_f32 v[38:39], v[30:31], v[38:39], v[42:43] op_sel:[0,0,1] op_sel_hi:[0,1,0] neg_lo:[0,0,1] neg_hi:[0,0,1]
	v_fma_f32 v42, v32, s39, -v30
	v_fma_f32 v38, v30, 0, -v32
	v_pk_mul_f32 v[56:57], v[42:43], v[50:51] op_sel_hi:[0,1]
	v_pk_fma_f32 v[58:59], v[38:39], v[50:51], v[56:57] op_sel:[0,0,1] op_sel_hi:[0,1,0] neg_lo:[0,0,1]
	v_pk_add_f32 v[50:51], v[118:119], v[48:49]
	v_pk_add_f32 v[48:49], v[48:49], v[118:119] neg_lo:[0,1] neg_hi:[0,1]
	v_mov_b32_e32 v53, v39
	v_pk_mul_f32 v[56:57], v[32:33], v[48:49] op_sel_hi:[0,1]
	v_pk_fma_f32 v[64:65], v[30:31], v[48:49], v[56:57] op_sel:[0,0,1] op_sel_hi:[0,1,0] neg_hi:[0,0,1]
	v_pk_add_f32 v[56:57], v[62:63], v[122:123] neg_lo:[0,1] neg_hi:[0,1]
	v_pk_add_f32 v[48:49], v[62:63], v[122:123]
	v_pk_mul_f32 v[62:63], v[42:43], v[56:57] op_sel_hi:[0,1]
	v_pk_fma_f32 v[114:115], v[38:39], v[56:57], v[62:63] op_sel:[0,0,1] op_sel_hi:[0,1,0] neg_lo:[0,0,1]
	v_pk_add_f32 v[56:57], v[22:23], v[40:41]
	v_pk_add_f32 v[22:23], v[40:41], v[22:23] neg_lo:[0,1] neg_hi:[0,1]
	s_nop 0
	v_pk_mul_f32 v[40:41], v[32:33], v[22:23] op_sel_hi:[0,1]
	v_pk_fma_f32 v[62:63], v[30:31], v[22:23], v[40:41] op_sel:[0,0,1] op_sel_hi:[0,1,0] neg_hi:[0,0,1]
	v_pk_add_f32 v[22:23], v[2:3], v[20:21]
	v_pk_add_f32 v[2:3], v[2:3], v[20:21] neg_lo:[0,1] neg_hi:[0,1]
	s_nop 0
	v_pk_mul_f32 v[20:21], v[42:43], v[2:3] op_sel_hi:[0,1]
	v_pk_fma_f32 v[40:41], v[38:39], v[2:3], v[20:21] op_sel:[0,0,1] op_sel_hi:[0,1,0] neg_lo:[0,0,1]
	v_pk_add_f32 v[20:21], v[60:61], v[46:47] neg_lo:[0,1] neg_hi:[0,1]
	v_pk_mul_f32 v[32:33], v[32:33], v[20:21] op_sel_hi:[0,1]
	v_pk_add_f32 v[2:3], v[46:47], v[60:61]
	v_pk_fma_f32 v[46:47], v[30:31], v[20:21], v[32:33] op_sel:[0,0,1] op_sel_hi:[0,1,0] neg_hi:[0,0,1]
	v_pk_add_f32 v[30:31], v[44:45], v[36:37] neg_lo:[0,1] neg_hi:[0,1]
	v_pk_mul_f32 v[32:33], v[42:43], v[30:31] op_sel_hi:[0,1]
	v_pk_add_f32 v[20:21], v[44:45], v[36:37]
	v_pk_fma_f32 v[36:37], v[38:39], v[30:31], v[32:33] op_sel:[0,0,1] op_sel_hi:[1,1,0] neg_lo:[0,0,1] neg_hi:[0,0,1]
	v_pk_fma_f32 v[30:31], v[38:39], v[30:31], v[32:33] op_sel:[0,0,1] op_sel_hi:[0,1,0]
	v_lshlrev_b32_e32 v30, 3, v79
	v_cvt_f32_u32_e32 v30, v30
	v_mov_b32_e32 v37, v31
	v_pk_add_f32 v[38:39], v[54:55], v[34:35]
	v_pk_add_f32 v[34:35], v[34:35], v[54:55] neg_lo:[0,1] neg_hi:[0,1]
	v_mul_f32_e32 v31, 0x38800000, v30
	v_sin_f32_e32 v32, v31
	v_cos_f32_e32 v30, v31
	v_pk_mul_f32 v[42:43], v[32:33], v[34:35] op_sel_hi:[0,1]
	v_pk_fma_f32 v[44:45], v[30:31], v[34:35], v[42:43] op_sel:[0,0,1] op_sel_hi:[0,1,0] neg_hi:[0,0,1]
	v_pk_add_f32 v[42:43], v[52:53], v[58:59] neg_lo:[0,1] neg_hi:[0,1]
	v_pk_add_f32 v[34:35], v[58:59], v[52:53]
	v_pk_mul_f32 v[52:53], v[32:33], v[42:43] op_sel_hi:[0,1]
	v_pk_fma_f32 v[54:55], v[30:31], v[42:43], v[52:53] op_sel:[0,0,1] op_sel_hi:[0,1,0] neg_hi:[0,0,1]
	v_pk_add_f32 v[42:43], v[48:49], v[50:51]
	v_pk_add_f32 v[48:49], v[50:51], v[48:49] neg_lo:[0,1] neg_hi:[0,1]
	s_nop 0
	v_pk_mul_f32 v[50:51], v[32:33], v[48:49] op_sel_hi:[0,1]
	v_pk_fma_f32 v[52:53], v[30:31], v[48:49], v[50:51] op_sel:[0,0,1] op_sel_hi:[0,1,0] neg_hi:[0,0,1]
	v_pk_add_f32 v[50:51], v[64:65], v[114:115] neg_lo:[0,1] neg_hi:[0,1]
	v_pk_mul_f32 v[58:59], v[32:33], v[50:51] op_sel_hi:[0,1]
	v_pk_fma_f32 v[60:61], v[30:31], v[50:51], v[58:59] op_sel:[0,0,1] op_sel_hi:[0,1,0] neg_hi:[0,0,1]
	v_pk_add_f32 v[50:51], v[22:23], v[56:57]
	v_pk_add_f32 v[22:23], v[56:57], v[22:23] neg_lo:[0,1] neg_hi:[0,1]
	v_pk_add_f32 v[48:49], v[114:115], v[64:65]
	v_pk_mul_f32 v[56:57], v[32:33], v[22:23] op_sel_hi:[0,1]
	v_pk_fma_f32 v[58:59], v[30:31], v[22:23], v[56:57] op_sel:[0,0,1] op_sel_hi:[0,1,0] neg_hi:[0,0,1]
	v_pk_add_f32 v[22:23], v[40:41], v[62:63]
	v_pk_add_f32 v[40:41], v[62:63], v[40:41] neg_lo:[0,1] neg_hi:[0,1]
	s_nop 0
	v_pk_mul_f32 v[56:57], v[32:33], v[40:41] op_sel_hi:[0,1]
	v_pk_fma_f32 v[62:63], v[30:31], v[40:41], v[56:57] op_sel:[0,0,1] op_sel_hi:[0,1,0] neg_hi:[0,0,1]
	v_pk_add_f32 v[40:41], v[2:3], v[20:21] neg_lo:[0,1] neg_hi:[0,1]
	v_pk_add_f32 v[2:3], v[20:21], v[2:3]
	v_pk_mul_f32 v[56:57], v[32:33], v[40:41] op_sel_hi:[0,1]
	v_pk_add_f32 v[20:21], v[36:37], v[46:47]
	v_pk_add_f32 v[36:37], v[46:47], v[36:37] neg_lo:[0,1] neg_hi:[0,1]
	v_pk_fma_f32 v[64:65], v[30:31], v[40:41], v[56:57] op_sel:[0,0,1] op_sel_hi:[0,1,0] neg_hi:[0,0,1]
	v_pk_mul_f32 v[32:33], v[32:33], v[36:37] op_sel_hi:[0,1]
	v_pk_fma_f32 v[40:41], v[30:31], v[36:37], v[32:33] op_sel:[0,0,1] op_sel_hi:[0,1,0] neg_hi:[0,0,1]
	ds_write_b64 v66, v[38:39]
	ds_write_b64 v67, v[44:45] offset:8192
	ds_write_b64 v68, v[34:35] offset:16384
	ds_write_b64 v69, v[54:55] offset:24576
	ds_write_b64 v70, v[42:43] offset:32768
	ds_write_b64 v71, v[52:53] offset:40960
	ds_write_b64 v72, v[48:49] offset:49152
	ds_write_b64 v73, v[60:61] offset:57344
	ds_write_b64 v74, v[50:51]
	ds_write_b64 v75, v[58:59]
	ds_write_b64 v76, v[22:23]
	ds_write_b64 v77, v[62:63]
	ds_write_b64 v78, v[2:3]
	ds_write_b64 v80, v[64:65]
	ds_write_b64 v81, v[20:21]
	ds_write_b64 v82, v[40:41]
	v_add_u32_e32 v2, 0x200, v25
	v_mov_b32_e32 v25, v2
	s_andn2_b64 exec, exec, s[10:11]
	s_cbranch_execnz .LBB0_643

.LBB0_646:
	v_and_or_b32 v140, v111, s42, v0
	v_or_b32_e32 v128, 0x200, v140
	v_ashrrev_i32_e32 v114, 5, v140
	v_lshl_add_u32 v141, v140, 3, 0
	v_ashrrev_i32_e32 v128, 5, v128
	v_lshl_add_u32 v152, v114, 3, v141
	v_or_b32_e32 v114, 64, v140
	v_or_b32_e32 v116, 0x80, v140
	v_or_b32_e32 v118, 0xc0, v140
	v_or_b32_e32 v120, 0x100, v140
	v_or_b32_e32 v122, 0x140, v140
	v_or_b32_e32 v124, 0x180, v140
	v_or_b32_e32 v126, 0x1c0, v140
	v_lshl_add_u32 v160, v128, 3, v141
	v_or_b32_e32 v128, 0x240, v140
	v_or_b32_e32 v130, 0x280, v140
	v_or_b32_e32 v132, 0x2c0, v140
	v_or_b32_e32 v134, 0x300, v140
	v_or_b32_e32 v136, 0x340, v140
	v_or_b32_e32 v138, 0x380, v140
	v_or_b32_e32 v140, 0x3c0, v140
	v_ashrrev_i32_e32 v114, 5, v114
	v_ashrrev_i32_e32 v116, 5, v116
	v_ashrrev_i32_e32 v118, 5, v118
	v_ashrrev_i32_e32 v120, 5, v120
	v_ashrrev_i32_e32 v122, 5, v122
	v_ashrrev_i32_e32 v124, 5, v124
	v_ashrrev_i32_e32 v126, 5, v126
	v_ashrrev_i32_e32 v128, 5, v128
	v_ashrrev_i32_e32 v130, 5, v130
	v_ashrrev_i32_e32 v132, 5, v132
	v_ashrrev_i32_e32 v134, 5, v134
	v_ashrrev_i32_e32 v136, 5, v136
	v_ashrrev_i32_e32 v138, 5, v138
	v_ashrrev_i32_e32 v140, 5, v140
	v_lshl_add_u32 v153, v114, 3, v141
	v_lshl_add_u32 v154, v116, 3, v141
	v_lshl_add_u32 v155, v118, 3, v141
	v_lshl_add_u32 v156, v120, 3, v141
	v_lshl_add_u32 v157, v122, 3, v141
	v_lshl_add_u32 v158, v124, 3, v141
	v_lshl_add_u32 v159, v126, 3, v141
	v_lshl_add_u32 v161, v128, 3, v141
	v_lshl_add_u32 v162, v130, 3, v141
	v_lshl_add_u32 v163, v132, 3, v141
	v_lshl_add_u32 v164, v134, 3, v141
	v_lshl_add_u32 v165, v136, 3, v141
	v_lshl_add_u32 v166, v138, 3, v141
	v_lshl_add_u32 v167, v140, 3, v141
	ds_read_b64 v[114:115], v153 offset:512
	ds_read_b64 v[116:117], v154 offset:1024
	ds_read_b64 v[118:119], v155 offset:1536
	ds_read_b64 v[120:121], v156 offset:2048
	ds_read_b64 v[122:123], v157 offset:2560
	ds_read_b64 v[124:125], v158 offset:3072
	ds_read_b64 v[126:127], v159 offset:3584
	ds_read_b64 v[128:129], v161 offset:4608
	ds_read_b64 v[130:131], v162 offset:5120
	ds_read_b64 v[132:133], v163 offset:5632
	ds_read_b64 v[134:135], v164 offset:6144
	ds_read_b64 v[136:137], v165 offset:6656
	ds_read_b64 v[138:139], v166 offset:7168
	ds_read_b64 v[140:141], v167 offset:7680
	ds_read_b64 v[142:143], v160 offset:4096
	ds_read_b64 v[144:145], v152
	v_add_u32_e32 v25, 0x200, v25
	v_cmp_lt_i32_e32 vcc, s35, v25
	v_add_u32_e32 v111, 0x2000, v111
	s_or_b64 s[10:11], vcc, s[10:11]
	s_waitcnt lgkmcnt(0)
	v_pk_add_f32 v[146:147], v[142:143], v[144:145]
	v_pk_add_f32 v[142:143], v[144:145], v[142:143] neg_lo:[0,1] neg_hi:[0,1]
	s_nop 0
	v_pk_mul_f32 v[144:145], v[20:21], v[142:143] op_sel:[0,1] op_sel_hi:[1,0]
	s_nop 0
	v_pk_fma_f32 v[148:149], v[2:3], v[142:143], v[144:145] neg_hi:[0,0,1]
	v_pk_add_f32 v[142:143], v[114:115], v[128:129]
	v_pk_add_f32 v[114:115], v[114:115], v[128:129] neg_lo:[0,1] neg_hi:[0,1]
	s_nop 0
	v_pk_mul_f32 v[128:129], v[40:41], v[114:115] op_sel:[0,1] op_sel_hi:[1,0]
	s_nop 0
	v_pk_fma_f32 v[144:145], v[38:39], v[114:115], v[128:129] neg_lo:[0,0,1]
	v_pk_add_f32 v[114:115], v[116:117], v[130:131]
	v_pk_add_f32 v[116:117], v[116:117], v[130:131] neg_lo:[0,1] neg_hi:[0,1]
	s_nop 0
	v_pk_mul_f32 v[128:129], v[44:45], v[116:117] op_sel:[0,1] op_sel_hi:[1,0]
	s_nop 0
	v_pk_fma_f32 v[130:131], v[42:43], v[116:117], v[128:129] neg_lo:[0,0,1]
	v_pk_add_f32 v[116:117], v[118:119], v[132:133]
	v_pk_add_f32 v[118:119], v[118:119], v[132:133] neg_lo:[0,1] neg_hi:[0,1]
	s_nop 0
	v_pk_mul_f32 v[128:129], v[48:49], v[118:119] op_sel:[0,1] op_sel_hi:[1,0]
	s_nop 0
	v_pk_fma_f32 v[132:133], v[32:33], v[118:119], v[128:129] neg_lo:[0,0,1]
	v_pk_add_f32 v[118:119], v[120:121], v[134:135]
	v_pk_add_f32 v[120:121], v[120:121], v[134:135] neg_lo:[0,1] neg_hi:[0,1]
	s_nop 0
	v_pk_mul_f32 v[128:129], v[52:53], v[120:121] op_sel:[0,1] op_sel_hi:[1,0]
	s_nop 0
	v_pk_fma_f32 v[134:135], v[50:51], v[120:121], v[128:129] neg_lo:[0,0,1]
	v_pk_add_f32 v[120:121], v[122:123], v[136:137]
	v_pk_add_f32 v[122:123], v[122:123], v[136:137] neg_lo:[0,1] neg_hi:[0,1]
	s_nop 0
	v_pk_mul_f32 v[128:129], v[22:23], v[122:123] op_sel:[0,1] op_sel_hi:[1,0]
	s_nop 0
	v_pk_fma_f32 v[136:137], v[46:47], v[122:123], v[128:129] neg_lo:[0,0,1]
	v_pk_add_f32 v[122:123], v[124:125], v[138:139]
	v_pk_add_f32 v[124:125], v[124:125], v[138:139] neg_lo:[0,1] neg_hi:[0,1]
	s_nop 0
	v_pk_mul_f32 v[128:129], v[34:35], v[124:125] op_sel:[0,1] op_sel_hi:[1,0]
	s_nop 0
	v_pk_fma_f32 v[138:139], v[36:37], v[124:125], v[128:129] neg_lo:[0,0,1]
	v_pk_add_f32 v[124:125], v[126:127], v[140:141]
	v_pk_add_f32 v[126:127], v[126:127], v[140:141] neg_lo:[0,1] neg_hi:[0,1]
	s_nop 0
	v_pk_mul_f32 v[128:129], v[58:59], v[126:127] op_sel:[0,1] op_sel_hi:[1,0]
	s_nop 0
	v_pk_fma_f32 v[140:141], v[30:31], v[126:127], v[128:129] neg_lo:[0,0,1]
	v_pk_add_f32 v[126:127], v[118:119], v[146:147]
	v_pk_add_f32 v[118:119], v[146:147], v[118:119] neg_lo:[0,1] neg_hi:[0,1]
	s_nop 0
	v_pk_mul_f32 v[128:129], v[56:57], v[118:119]
	s_nop 0
	v_pk_fma_f32 v[146:147], v[54:55], v[118:119], v[128:129] op_sel:[0,0,1] op_sel_hi:[1,1,0] neg_hi:[0,0,1]
	v_pk_add_f32 v[118:119], v[142:143], v[120:121]
	v_pk_add_f32 v[120:121], v[142:143], v[120:121] neg_lo:[0,1] neg_hi:[0,1]
	s_nop 0
	v_pk_mul_f32 v[128:129], v[66:67], v[120:121]
	s_nop 0
	v_pk_fma_f32 v[142:143], v[64:65], v[120:121], v[128:129] op_sel:[0,0,1] op_sel_hi:[1,1,0] neg_lo:[0,0,1]
	v_pk_add_f32 v[120:121], v[114:115], v[122:123]
	v_pk_add_f32 v[114:115], v[114:115], v[122:123] neg_lo:[0,1] neg_hi:[0,1]
	s_nop 0
	v_pk_mul_f32 v[122:123], v[70:71], v[114:115]
	s_nop 0
	v_pk_fma_f32 v[128:129], v[68:69], v[114:115], v[122:123] op_sel:[0,0,1] op_sel_hi:[1,1,0] neg_lo:[0,0,1]
	v_pk_add_f32 v[114:115], v[116:117], v[124:125]
	v_pk_add_f32 v[116:117], v[116:117], v[124:125] neg_lo:[0,1] neg_hi:[0,1]
	s_nop 0
	v_pk_mul_f32 v[122:123], v[60:61], v[116:117]
	s_nop 0
	v_pk_fma_f32 v[124:125], v[62:63], v[116:117], v[122:123] op_sel:[0,0,1] op_sel_hi:[1,1,0] neg_lo:[0,0,1]
	v_pk_add_f32 v[122:123], v[148:149], v[134:135] neg_lo:[0,1] neg_hi:[0,1]
	v_pk_add_f32 v[116:117], v[134:135], v[148:149]
	v_pk_mul_f32 v[134:135], v[56:57], v[122:123]
	s_nop 0
	v_pk_fma_f32 v[148:149], v[54:55], v[122:123], v[134:135] op_sel:[0,0,1] op_sel_hi:[1,1,0] neg_hi:[0,0,1]
	v_pk_add_f32 v[134:135], v[144:145], v[136:137] neg_lo:[0,1] neg_hi:[0,1]
	v_pk_add_f32 v[122:123], v[144:145], v[136:137]
	v_pk_mul_f32 v[136:137], v[66:67], v[134:135]
	s_nop 0
	v_pk_fma_f32 v[144:145], v[64:65], v[134:135], v[136:137] op_sel:[0,0,1] op_sel_hi:[1,1,0] neg_lo:[0,0,1]
	v_pk_add_f32 v[134:135], v[130:131], v[138:139]
	v_pk_add_f32 v[130:131], v[130:131], v[138:139] neg_lo:[0,1] neg_hi:[0,1]
	s_nop 0
	v_pk_mul_f32 v[136:137], v[70:71], v[130:131]
	s_nop 0
	v_pk_fma_f32 v[138:139], v[68:69], v[130:131], v[136:137] op_sel:[0,0,1] op_sel_hi:[1,1,0] neg_lo:[0,0,1]
	v_pk_add_f32 v[130:131], v[132:133], v[140:141]
	v_pk_add_f32 v[132:133], v[132:133], v[140:141] neg_lo:[0,1] neg_hi:[0,1]
	s_nop 0
	v_pk_mul_f32 v[136:137], v[60:61], v[132:133]
	s_nop 0
	v_pk_fma_f32 v[140:141], v[62:63], v[132:133], v[136:137] op_sel:[0,0,1] op_sel_hi:[1,1,0] neg_lo:[0,0,1]
	v_pk_add_f32 v[132:133], v[120:121], v[126:127]
	v_pk_add_f32 v[120:121], v[126:127], v[120:121] neg_lo:[0,1] neg_hi:[0,1]
	s_nop 0
	v_pk_mul_f32 v[126:127], v[74:75], v[120:121]
	s_nop 0
	v_pk_fma_f32 v[136:137], v[72:73], v[120:121], v[126:127] op_sel:[0,0,1] op_sel_hi:[1,1,0] neg_hi:[0,0,1]
	v_pk_add_f32 v[120:121], v[118:119], v[114:115]
	v_pk_add_f32 v[114:115], v[118:119], v[114:115] neg_lo:[0,1] neg_hi:[0,1]
	s_nop 0
	v_pk_mul_f32 v[118:119], v[78:79], v[114:115]
	s_nop 0
	v_pk_fma_f32 v[126:127], v[76:77], v[114:115], v[118:119] op_sel:[0,0,1] op_sel_hi:[1,1,0] neg_lo:[0,0,1]
	v_pk_add_f32 v[118:119], v[146:147], v[128:129] neg_lo:[0,1] neg_hi:[0,1]
	v_pk_add_f32 v[114:115], v[128:129], v[146:147]
	v_pk_mul_f32 v[128:129], v[74:75], v[118:119]
	s_nop 0
	v_pk_fma_f32 v[146:147], v[72:73], v[118:119], v[128:129] op_sel:[0,0,1] op_sel_hi:[1,1,0] neg_hi:[0,0,1]
	v_pk_add_f32 v[118:119], v[142:143], v[124:125]
	v_pk_add_f32 v[124:125], v[142:143], v[124:125] neg_lo:[0,1] neg_hi:[0,1]
	s_nop 0
	v_pk_mul_f32 v[128:129], v[78:79], v[124:125]
	s_nop 0
	v_pk_fma_f32 v[142:143], v[76:77], v[124:125], v[128:129] op_sel:[0,0,1] op_sel_hi:[1,1,0] neg_lo:[0,0,1]
	v_pk_add_f32 v[124:125], v[134:135], v[116:117]
	v_pk_add_f32 v[116:117], v[116:117], v[134:135] neg_lo:[0,1] neg_hi:[0,1]
	s_nop 0
	v_pk_mul_f32 v[128:129], v[74:75], v[116:117]
	s_nop 0
	v_pk_fma_f32 v[134:135], v[72:73], v[116:117], v[128:129] op_sel:[0,0,1] op_sel_hi:[1,1,0] neg_hi:[0,0,1]
	v_pk_add_f32 v[116:117], v[122:123], v[130:131]
	v_pk_add_f32 v[122:123], v[122:123], v[130:131] neg_lo:[0,1] neg_hi:[0,1]
	s_nop 0
	v_pk_mul_f32 v[128:129], v[78:79], v[122:123]
	s_nop 0
	v_pk_fma_f32 v[130:131], v[76:77], v[122:123], v[128:129] op_sel:[0,0,1] op_sel_hi:[1,1,0] neg_lo:[0,0,1]
	v_pk_add_f32 v[128:129], v[148:149], v[138:139] neg_lo:[0,1] neg_hi:[0,1]
	v_pk_add_f32 v[122:123], v[138:139], v[148:149]
	v_pk_mul_f32 v[138:139], v[74:75], v[128:129]
	s_nop 0
	v_pk_fma_f32 v[148:149], v[72:73], v[128:129], v[138:139] op_sel:[0,0,1] op_sel_hi:[1,1,0] neg_hi:[0,0,1]
	v_pk_add_f32 v[138:139], v[144:145], v[140:141] neg_lo:[0,1] neg_hi:[0,1]
	v_pk_add_f32 v[128:129], v[144:145], v[140:141]
	v_pk_mul_f32 v[140:141], v[78:79], v[138:139]
	s_nop 0
	v_pk_fma_f32 v[144:145], v[76:77], v[138:139], v[140:141] op_sel:[0,0,1] op_sel_hi:[1,1,0] neg_lo:[0,0,1]
	v_pk_add_f32 v[138:139], v[120:121], v[132:133]
	v_pk_add_f32 v[120:121], v[132:133], v[120:121] neg_lo:[0,1] neg_hi:[0,1]
	s_nop 0
	v_pk_mul_f32 v[132:133], v[82:83], v[120:121]
	s_nop 0
	v_pk_fma_f32 v[140:141], v[80:81], v[120:121], v[132:133] op_sel:[0,0,1] op_sel_hi:[1,1,0] neg_hi:[0,0,1]
	v_pk_add_f32 v[120:121], v[126:127], v[136:137]
	v_pk_add_f32 v[126:127], v[136:137], v[126:127] neg_lo:[0,1] neg_hi:[0,1]
	s_nop 0
	v_pk_mul_f32 v[132:133], v[82:83], v[126:127]
	s_nop 0
	v_pk_fma_f32 v[136:137], v[80:81], v[126:127], v[132:133] op_sel:[0,0,1] op_sel_hi:[1,1,0] neg_hi:[0,0,1]
	v_pk_add_f32 v[126:127], v[118:119], v[114:115]
	v_pk_add_f32 v[114:115], v[114:115], v[118:119] neg_lo:[0,1] neg_hi:[0,1]
	s_nop 0
	v_pk_mul_f32 v[118:119], v[82:83], v[114:115]
	s_nop 0
	v_pk_fma_f32 v[132:133], v[80:81], v[114:115], v[118:119] op_sel:[0,0,1] op_sel_hi:[1,1,0] neg_hi:[0,0,1]
	v_pk_add_f32 v[118:119], v[146:147], v[142:143] neg_lo:[0,1] neg_hi:[0,1]
	v_pk_add_f32 v[114:115], v[142:143], v[146:147]
	v_pk_mul_f32 v[142:143], v[82:83], v[118:119]
	s_nop 0
	v_pk_fma_f32 v[146:147], v[80:81], v[118:119], v[142:143] op_sel:[0,0,1] op_sel_hi:[1,1,0] neg_hi:[0,0,1]
	v_pk_add_f32 v[118:119], v[116:117], v[124:125]
	v_pk_add_f32 v[116:117], v[124:125], v[116:117] neg_lo:[0,1] neg_hi:[0,1]
	s_nop 0
	v_pk_mul_f32 v[124:125], v[82:83], v[116:117]
	s_nop 0
	v_pk_fma_f32 v[142:143], v[80:81], v[116:117], v[124:125] op_sel:[0,0,1] op_sel_hi:[1,1,0] neg_hi:[0,0,1]
	v_pk_add_f32 v[124:125], v[134:135], v[130:131] neg_lo:[0,1] neg_hi:[0,1]
	v_pk_add_f32 v[116:117], v[130:131], v[134:135]
	v_pk_mul_f32 v[130:131], v[82:83], v[124:125]
	s_nop 0
	v_pk_fma_f32 v[134:135], v[80:81], v[124:125], v[130:131] op_sel:[0,0,1] op_sel_hi:[1,1,0] neg_hi:[0,0,1]
	v_pk_add_f32 v[124:125], v[122:123], v[128:129] neg_lo:[0,1] neg_hi:[0,1]
	v_pk_add_f32 v[122:123], v[128:129], v[122:123]
	v_pk_mul_f32 v[130:131], v[82:83], v[124:125]
	v_pk_add_f32 v[128:129], v[148:149], v[144:145] neg_lo:[0,1] neg_hi:[0,1]
	v_pk_fma_f32 v[150:151], v[80:81], v[124:125], v[130:131] op_sel:[0,0,1] op_sel_hi:[1,1,0] neg_hi:[0,0,1]
	v_pk_mul_f32 v[130:131], v[82:83], v[128:129]
	v_pk_add_f32 v[124:125], v[144:145], v[148:149]
	v_pk_fma_f32 v[144:145], v[80:81], v[128:129], v[130:131] op_sel:[0,0,1] op_sel_hi:[1,1,0] neg_hi:[0,0,1]
	ds_write_b64 v152, v[138:139]
	ds_write_b64 v153, v[140:141] offset:512
	ds_write_b64 v154, v[120:121] offset:1024
	ds_write_b64 v155, v[136:137] offset:1536
	ds_write_b64 v156, v[126:127] offset:2048
	ds_write_b64 v157, v[132:133] offset:2560
	ds_write_b64 v158, v[114:115] offset:3072
	ds_write_b64 v159, v[146:147] offset:3584
	ds_write_b64 v160, v[118:119] offset:4096
	ds_write_b64 v161, v[142:143] offset:4608
	ds_write_b64 v162, v[116:117] offset:5120
	ds_write_b64 v163, v[134:135] offset:5632
	ds_write_b64 v164, v[122:123] offset:6144
	ds_write_b64 v165, v[150:151] offset:6656
	ds_write_b64 v166, v[124:125] offset:7168
	ds_write_b64 v167, v[144:145] offset:7680
	s_andn2_b64 exec, exec, s[10:11]
	s_cbranch_execnz .LBB0_646

.LBB0_649:
	v_and_b32_e32 v130, 0xffffffc0, v111
	v_or_b32_e32 v114, v130, v0
	v_lshl_add_u32 v131, v114, 3, 0
	v_ashrrev_i32_e32 v114, 2, v130
	v_or_b32_e32 v130, 32, v130
	v_ashrrev_i32_e32 v130, 5, v130
	v_add_u32_e32 v152, v131, v114
	v_lshl_add_u32 v153, v130, 3, v131
	ds_read2_b64 v[114:117], v152 offset1:4
	ds_read2_b64 v[118:121], v152 offset0:8 offset1:12
	ds_read2_b64 v[122:125], v152 offset0:16 offset1:20
	ds_read2_b64 v[126:129], v152 offset0:24 offset1:28
	ds_read2_b64 v[130:133], v153 offset0:32 offset1:36
	ds_read2_b64 v[134:137], v153 offset0:40 offset1:44
	ds_read2_b64 v[138:141], v153 offset0:48 offset1:52
	ds_read2_b64 v[142:145], v153 offset0:56 offset1:60
	v_add_u32_e32 v25, 0x200, v25
	s_waitcnt lgkmcnt(3)
	v_pk_add_f32 v[146:147], v[130:131], v[114:115]
	v_pk_add_f32 v[114:115], v[114:115], v[130:131] neg_lo:[0,1] neg_hi:[0,1]
	v_cmp_lt_i32_e32 vcc, s35, v25
	v_pk_mul_f32 v[130:131], v[20:21], v[114:115] op_sel:[0,1] op_sel_hi:[1,0]
	v_add_u32_e32 v111, 0x2000, v111
	v_pk_fma_f32 v[148:149], v[2:3], v[114:115], v[130:131] neg_hi:[0,0,1]
	s_or_b64 s[10:11], vcc, s[10:11]
	v_pk_add_f32 v[114:115], v[116:117], v[132:133]
	v_pk_add_f32 v[116:117], v[116:117], v[132:133] neg_lo:[0,1] neg_hi:[0,1]
	s_nop 0
	v_pk_mul_f32 v[130:131], v[40:41], v[116:117] op_sel:[0,1] op_sel_hi:[1,0]
	s_nop 0
	v_pk_fma_f32 v[132:133], v[38:39], v[116:117], v[130:131] neg_lo:[0,0,1]
	s_waitcnt lgkmcnt(2)
	v_pk_add_f32 v[116:117], v[118:119], v[134:135]
	v_pk_add_f32 v[118:119], v[118:119], v[134:135] neg_lo:[0,1] neg_hi:[0,1]
	s_nop 0
	v_pk_mul_f32 v[130:131], v[44:45], v[118:119] op_sel:[0,1] op_sel_hi:[1,0]
	s_nop 0
	v_pk_fma_f32 v[134:135], v[42:43], v[118:119], v[130:131] neg_lo:[0,0,1]
	v_pk_add_f32 v[118:119], v[120:121], v[136:137]
	v_pk_add_f32 v[120:121], v[120:121], v[136:137] neg_lo:[0,1] neg_hi:[0,1]
	s_nop 0
	v_pk_mul_f32 v[130:131], v[48:49], v[120:121] op_sel:[0,1] op_sel_hi:[1,0]
	s_nop 0
	v_pk_fma_f32 v[136:137], v[32:33], v[120:121], v[130:131] neg_lo:[0,0,1]
	s_waitcnt lgkmcnt(1)
	v_pk_add_f32 v[120:121], v[122:123], v[138:139]
	v_pk_add_f32 v[122:123], v[122:123], v[138:139] neg_lo:[0,1] neg_hi:[0,1]
	s_nop 0
	v_pk_mul_f32 v[130:131], v[52:53], v[122:123] op_sel:[0,1] op_sel_hi:[1,0]
	s_nop 0
	v_pk_fma_f32 v[138:139], v[50:51], v[122:123], v[130:131] neg_lo:[0,0,1]
	v_pk_add_f32 v[122:123], v[124:125], v[140:141]
	v_pk_add_f32 v[124:125], v[124:125], v[140:141] neg_lo:[0,1] neg_hi:[0,1]
	s_nop 0
	v_pk_mul_f32 v[130:131], v[22:23], v[124:125] op_sel:[0,1] op_sel_hi:[1,0]
	s_nop 0
	v_pk_fma_f32 v[140:141], v[46:47], v[124:125], v[130:131] neg_lo:[0,0,1]
	s_waitcnt lgkmcnt(0)
	v_pk_add_f32 v[124:125], v[126:127], v[142:143]
	v_pk_add_f32 v[126:127], v[126:127], v[142:143] neg_lo:[0,1] neg_hi:[0,1]
	s_nop 0
	v_pk_mul_f32 v[130:131], v[34:35], v[126:127] op_sel:[0,1] op_sel_hi:[1,0]
	s_nop 0
	v_pk_fma_f32 v[142:143], v[36:37], v[126:127], v[130:131] neg_lo:[0,0,1]
	v_pk_add_f32 v[126:127], v[128:129], v[144:145]
	v_pk_add_f32 v[128:129], v[128:129], v[144:145] neg_lo:[0,1] neg_hi:[0,1]
	s_nop 0
	v_pk_mul_f32 v[130:131], v[58:59], v[128:129] op_sel:[0,1] op_sel_hi:[1,0]
	s_nop 0
	v_pk_fma_f32 v[144:145], v[30:31], v[128:129], v[130:131] neg_lo:[0,0,1]
	v_pk_add_f32 v[128:129], v[120:121], v[146:147]
	v_pk_add_f32 v[120:121], v[146:147], v[120:121] neg_lo:[0,1] neg_hi:[0,1]
	s_nop 0
	v_pk_mul_f32 v[130:131], v[56:57], v[120:121]
	s_nop 0
	v_pk_fma_f32 v[146:147], v[54:55], v[120:121], v[130:131] op_sel:[0,0,1] op_sel_hi:[1,1,0] neg_hi:[0,0,1]
	v_pk_add_f32 v[120:121], v[114:115], v[122:123]
	v_pk_add_f32 v[114:115], v[114:115], v[122:123] neg_lo:[0,1] neg_hi:[0,1]
	s_nop 0
	v_pk_mul_f32 v[122:123], v[66:67], v[114:115]
	s_nop 0
	v_pk_fma_f32 v[130:131], v[64:65], v[114:115], v[122:123] op_sel:[0,0,1] op_sel_hi:[1,1,0] neg_lo:[0,0,1]
	v_pk_add_f32 v[114:115], v[116:117], v[124:125]
	v_pk_add_f32 v[116:117], v[116:117], v[124:125] neg_lo:[0,1] neg_hi:[0,1]
	s_nop 0
	v_pk_mul_f32 v[122:123], v[70:71], v[116:117]
	s_nop 0
	v_pk_fma_f32 v[124:125], v[68:69], v[116:117], v[122:123] op_sel:[0,0,1] op_sel_hi:[1,1,0] neg_lo:[0,0,1]
	v_pk_add_f32 v[116:117], v[118:119], v[126:127]
	v_pk_add_f32 v[118:119], v[118:119], v[126:127] neg_lo:[0,1] neg_hi:[0,1]
	s_nop 0
	v_pk_mul_f32 v[122:123], v[60:61], v[118:119]
	s_nop 0
	v_pk_fma_f32 v[126:127], v[62:63], v[118:119], v[122:123] op_sel:[0,0,1] op_sel_hi:[1,1,0] neg_lo:[0,0,1]
	v_pk_add_f32 v[122:123], v[148:149], v[138:139] neg_lo:[0,1] neg_hi:[0,1]
	v_pk_add_f32 v[118:119], v[138:139], v[148:149]
	v_pk_mul_f32 v[138:139], v[56:57], v[122:123]
	s_nop 0
	v_pk_fma_f32 v[148:149], v[54:55], v[122:123], v[138:139] op_sel:[0,0,1] op_sel_hi:[1,1,0] neg_hi:[0,0,1]
	v_pk_add_f32 v[122:123], v[132:133], v[140:141]
	v_pk_add_f32 v[132:133], v[132:133], v[140:141] neg_lo:[0,1] neg_hi:[0,1]
	s_nop 0
	v_pk_mul_f32 v[138:139], v[66:67], v[132:133]
	s_nop 0
	v_pk_fma_f32 v[140:141], v[64:65], v[132:133], v[138:139] op_sel:[0,0,1] op_sel_hi:[1,1,0] neg_lo:[0,0,1]
	v_pk_add_f32 v[132:133], v[134:135], v[142:143]
	v_pk_add_f32 v[134:135], v[134:135], v[142:143] neg_lo:[0,1] neg_hi:[0,1]
	s_nop 0
	v_pk_mul_f32 v[138:139], v[70:71], v[134:135]
	s_nop 0
	v_pk_fma_f32 v[142:143], v[68:69], v[134:135], v[138:139] op_sel:[0,0,1] op_sel_hi:[1,1,0] neg_lo:[0,0,1]
	v_pk_add_f32 v[134:135], v[136:137], v[144:145]
	v_pk_add_f32 v[136:137], v[136:137], v[144:145] neg_lo:[0,1] neg_hi:[0,1]
	s_nop 0
	v_pk_mul_f32 v[138:139], v[60:61], v[136:137]
	s_nop 0
	v_pk_fma_f32 v[144:145], v[62:63], v[136:137], v[138:139] op_sel:[0,0,1] op_sel_hi:[1,1,0] neg_lo:[0,0,1]
	v_pk_add_f32 v[136:137], v[114:115], v[128:129]
	v_pk_add_f32 v[114:115], v[128:129], v[114:115] neg_lo:[0,1] neg_hi:[0,1]
	s_nop 0
	v_pk_mul_f32 v[128:129], v[74:75], v[114:115]
	s_nop 0
	v_pk_fma_f32 v[138:139], v[72:73], v[114:115], v[128:129] op_sel:[0,0,1] op_sel_hi:[1,1,0] neg_hi:[0,0,1]
	v_pk_add_f32 v[114:115], v[120:121], v[116:117]
	v_pk_add_f32 v[116:117], v[120:121], v[116:117] neg_lo:[0,1] neg_hi:[0,1]
	s_nop 0
	v_pk_mul_f32 v[120:121], v[78:79], v[116:117]
	s_nop 0
	v_pk_fma_f32 v[128:129], v[76:77], v[116:117], v[120:121] op_sel:[0,0,1] op_sel_hi:[1,1,0] neg_lo:[0,0,1]
	v_pk_add_f32 v[120:121], v[146:147], v[124:125] neg_lo:[0,1] neg_hi:[0,1]
	v_pk_add_f32 v[116:117], v[124:125], v[146:147]
	v_pk_mul_f32 v[124:125], v[74:75], v[120:121]
	s_nop 0
	v_pk_fma_f32 v[146:147], v[72:73], v[120:121], v[124:125] op_sel:[0,0,1] op_sel_hi:[1,1,0] neg_hi:[0,0,1]
	v_pk_add_f32 v[124:125], v[130:131], v[126:127] neg_lo:[0,1] neg_hi:[0,1]
	v_pk_add_f32 v[120:121], v[130:131], v[126:127]
	v_pk_mul_f32 v[126:127], v[78:79], v[124:125]
	s_nop 0
	v_pk_fma_f32 v[130:131], v[76:77], v[124:125], v[126:127] op_sel:[0,0,1] op_sel_hi:[1,1,0] neg_lo:[0,0,1]
	v_pk_add_f32 v[124:125], v[132:133], v[118:119]
	v_pk_add_f32 v[118:119], v[118:119], v[132:133] neg_lo:[0,1] neg_hi:[0,1]
	s_nop 0
	v_pk_mul_f32 v[126:127], v[74:75], v[118:119]
	s_nop 0
	v_pk_fma_f32 v[132:133], v[72:73], v[118:119], v[126:127] op_sel:[0,0,1] op_sel_hi:[1,1,0] neg_hi:[0,0,1]
	v_pk_add_f32 v[118:119], v[122:123], v[134:135]
	v_pk_add_f32 v[122:123], v[122:123], v[134:135] neg_lo:[0,1] neg_hi:[0,1]
	s_nop 0
	v_pk_mul_f32 v[126:127], v[78:79], v[122:123]
	s_nop 0
	v_pk_fma_f32 v[134:135], v[76:77], v[122:123], v[126:127] op_sel:[0,0,1] op_sel_hi:[1,1,0] neg_lo:[0,0,1]
	v_pk_add_f32 v[126:127], v[148:149], v[142:143] neg_lo:[0,1] neg_hi:[0,1]
	v_pk_add_f32 v[122:123], v[142:143], v[148:149]
	v_pk_mul_f32 v[142:143], v[74:75], v[126:127]
	s_nop 0
	v_pk_fma_f32 v[148:149], v[72:73], v[126:127], v[142:143] op_sel:[0,0,1] op_sel_hi:[1,1,0] neg_hi:[0,0,1]
	v_pk_add_f32 v[126:127], v[140:141], v[144:145]
	v_pk_add_f32 v[140:141], v[140:141], v[144:145] neg_lo:[0,1] neg_hi:[0,1]
	s_nop 0
	v_pk_mul_f32 v[142:143], v[78:79], v[140:141]
	s_nop 0
	v_pk_fma_f32 v[144:145], v[76:77], v[140:141], v[142:143] op_sel:[0,0,1] op_sel_hi:[1,1,0] neg_lo:[0,0,1]
	v_pk_add_f32 v[140:141], v[114:115], v[136:137]
	v_pk_add_f32 v[114:115], v[136:137], v[114:115] neg_lo:[0,1] neg_hi:[0,1]
	s_nop 0
	v_pk_mul_f32 v[136:137], v[82:83], v[114:115]
	s_nop 0
	v_pk_fma_f32 v[142:143], v[80:81], v[114:115], v[136:137] op_sel:[0,0,1] op_sel_hi:[1,1,0] neg_hi:[0,0,1]
	v_pk_add_f32 v[114:115], v[128:129], v[138:139]
	v_pk_add_f32 v[128:129], v[138:139], v[128:129] neg_lo:[0,1] neg_hi:[0,1]
	s_nop 0
	v_pk_mul_f32 v[136:137], v[82:83], v[128:129]
	s_nop 0
	v_pk_fma_f32 v[138:139], v[80:81], v[128:129], v[136:137] op_sel:[0,0,1] op_sel_hi:[1,1,0] neg_hi:[0,0,1]
	v_pk_add_f32 v[128:129], v[120:121], v[116:117]
	v_pk_add_f32 v[116:117], v[116:117], v[120:121] neg_lo:[0,1] neg_hi:[0,1]
	s_nop 0
	v_pk_mul_f32 v[120:121], v[82:83], v[116:117]
	s_nop 0
	v_pk_fma_f32 v[136:137], v[80:81], v[116:117], v[120:121] op_sel:[0,0,1] op_sel_hi:[1,1,0] neg_hi:[0,0,1]
	v_pk_add_f32 v[120:121], v[146:147], v[130:131] neg_lo:[0,1] neg_hi:[0,1]
	v_pk_add_f32 v[116:117], v[130:131], v[146:147]
	v_pk_mul_f32 v[130:131], v[82:83], v[120:121]
	s_nop 0
	v_pk_fma_f32 v[146:147], v[80:81], v[120:121], v[130:131] op_sel:[0,0,1] op_sel_hi:[1,1,0] neg_hi:[0,0,1]
	v_pk_add_f32 v[120:121], v[118:119], v[124:125]
	v_pk_add_f32 v[118:119], v[124:125], v[118:119] neg_lo:[0,1] neg_hi:[0,1]
	s_nop 0
	v_pk_mul_f32 v[124:125], v[82:83], v[118:119]
	s_nop 0
	v_pk_fma_f32 v[130:131], v[80:81], v[118:119], v[124:125] op_sel:[0,0,1] op_sel_hi:[1,1,0] neg_hi:[0,0,1]
	v_pk_add_f32 v[124:125], v[132:133], v[134:135] neg_lo:[0,1] neg_hi:[0,1]
	v_pk_add_f32 v[118:119], v[134:135], v[132:133]
	v_pk_mul_f32 v[132:133], v[82:83], v[124:125]
	s_nop 0
	v_pk_fma_f32 v[134:135], v[80:81], v[124:125], v[132:133] op_sel:[0,0,1] op_sel_hi:[1,1,0] neg_hi:[0,0,1]
	v_pk_add_f32 v[124:125], v[122:123], v[126:127] neg_lo:[0,1] neg_hi:[0,1]
	v_pk_add_f32 v[122:123], v[126:127], v[122:123]
	v_pk_mul_f32 v[132:133], v[82:83], v[124:125]
	v_pk_add_f32 v[126:127], v[148:149], v[144:145] neg_lo:[0,1] neg_hi:[0,1]
	v_pk_fma_f32 v[150:151], v[80:81], v[124:125], v[132:133] op_sel:[0,0,1] op_sel_hi:[1,1,0] neg_hi:[0,0,1]
	v_pk_mul_f32 v[132:133], v[82:83], v[126:127]
	v_pk_add_f32 v[124:125], v[144:145], v[148:149]
	v_pk_fma_f32 v[144:145], v[80:81], v[126:127], v[132:133] op_sel:[0,0,1] op_sel_hi:[1,1,0] neg_hi:[0,0,1]
	ds_write2_b64 v152, v[140:141], v[142:143] offset1:4
	ds_write2_b64 v152, v[114:115], v[138:139] offset0:8 offset1:12
	ds_write2_b64 v152, v[128:129], v[136:137] offset0:16 offset1:20
	ds_write2_b64 v152, v[116:117], v[146:147] offset0:24 offset1:28
	ds_write2_b64 v153, v[120:121], v[130:131] offset0:32 offset1:36
	ds_write2_b64 v153, v[118:119], v[134:135] offset0:40 offset1:44
	ds_write2_b64 v153, v[122:123], v[150:151] offset0:48 offset1:52
	ds_write2_b64 v153, v[124:125], v[144:145] offset0:56 offset1:60
	s_andn2_b64 exec, exec, s[10:11]
	s_cbranch_execnz .LBB0_649

.LBB0_652:
	v_ashrrev_i32_e32 v20, 5, v3
	v_lshl_add_u32 v25, v20, 3, v2
	ds_read2_b64 v[20:23], v25 offset1:1
	ds_read2_b64 v[30:33], v25 offset0:2 offset1:3
	v_add_u32_e32 v0, 0x200, v0
	v_cmp_lt_i32_e32 vcc, s43, v0
	v_add_u32_e32 v3, 0x800, v3
	v_add_u32_e32 v2, 0x4000, v2
	s_waitcnt lgkmcnt(0)
	v_pk_add_f32 v[34:35], v[30:31], v[20:21]
	v_pk_add_f32 v[20:21], v[20:21], v[30:31] neg_lo:[0,1] neg_hi:[0,1]
	v_pk_add_f32 v[30:31], v[22:23], v[32:33] neg_lo:[0,1] neg_hi:[0,1]
	v_pk_add_f32 v[22:23], v[22:23], v[32:33]
	v_pk_mul_f32 v[32:33], v[20:21], 0 op_sel_hi:[1,0]
	s_waitcnt vmcnt(0)
	v_pk_fma_f32 v[36:37], v[30:31], 0, v[30:31] op_sel:[0,0,1] op_sel_hi:[1,0,0] neg_hi:[0,0,1]
	v_pk_add_f32 v[38:39], v[34:35], v[22:23] neg_lo:[0,1] neg_hi:[0,1]
	v_pk_add_f32 v[22:23], v[22:23], v[34:35]
	v_pk_add_f32 v[34:35], v[20:21], v[32:33] op_sel:[0,1] op_sel_hi:[1,0]
	v_pk_add_f32 v[20:21], v[20:21], v[32:33] op_sel:[0,1] op_sel_hi:[1,0] neg_lo:[0,1] neg_hi:[0,1]
	v_pk_mul_f32 v[30:31], v[38:39], 0 op_sel_hi:[1,0]
	v_mov_b32_e32 v35, v21
	v_pk_add_f32 v[20:21], v[38:39], v[30:31] op_sel:[0,1] op_sel_hi:[1,0]
	v_pk_add_f32 v[30:31], v[38:39], v[30:31] op_sel:[0,1] op_sel_hi:[1,0] neg_lo:[0,1] neg_hi:[0,1]
	v_pk_add_f32 v[32:33], v[36:37], v[34:35]
	v_pk_add_f32 v[34:35], v[34:35], v[36:37] neg_lo:[0,1] neg_hi:[0,1]
	v_mov_b32_e32 v21, v31
	v_pk_mul_f32 v[30:31], v[34:35], 0 op_sel_hi:[1,0]
	ds_write2_b64 v25, v[22:23], v[20:21] offset1:1
	v_pk_add_f32 v[20:21], v[34:35], v[30:31] op_sel:[0,1] op_sel_hi:[1,0]
	v_pk_add_f32 v[22:23], v[34:35], v[30:31] op_sel:[0,1] op_sel_hi:[1,0] neg_lo:[0,1] neg_hi:[0,1]
	s_or_b64 s[10:11], vcc, s[10:11]
	v_mov_b32_e32 v21, v23
	ds_write2_b64 v25, v[32:33], v[20:21] offset0:2 offset1:3
	s_andn2_b64 exec, exec, s[10:11]
	s_cbranch_execnz .LBB0_652

.LBB0_663:
	v_and_b32_e32 v65, 0x3ff, v25
	v_and_or_b32 v56, v0, s38, v65
	v_or_b32_e32 v21, 0x400, v56
	v_lshl_add_u32 v20, v56, 3, 0
	v_ashrrev_i32_e32 v21, 5, v21
	v_lshl_add_u32 v58, v21, 3, v20
	v_or_b32_e32 v21, 0x800, v56
	v_ashrrev_i32_e32 v21, 5, v21
	v_lshl_add_u32 v59, v21, 3, v20
	v_or_b32_e32 v21, 0xc00, v56
	v_ashrrev_i32_e32 v21, 5, v21
	v_lshl_add_u32 v60, v21, 3, v20
	v_or_b32_e32 v21, 0x1000, v56
	v_ashrrev_i32_e32 v21, 5, v21
	v_lshl_add_u32 v61, v21, 3, v20
	v_or_b32_e32 v21, 0x1400, v56
	v_ashrrev_i32_e32 v21, 5, v21
	v_lshl_add_u32 v62, v21, 3, v20
	v_or_b32_e32 v21, 0x1800, v56
	v_ashrrev_i32_e32 v21, 5, v21
	v_lshl_add_u32 v63, v21, 3, v20
	v_or_b32_e32 v21, 0x1c00, v56
	v_ashrrev_i32_e32 v2, 5, v56
	v_ashrrev_i32_e32 v21, 5, v21
	v_lshl_add_u32 v57, v2, 3, v20
	v_lshl_add_u32 v64, v21, 3, v20
	v_cvt_f32_u32_e32 v20, v65
	ds_read_b64 v[2:3], v57
	ds_read_b64 v[22:23], v58 offset:8192
	ds_read_b64 v[42:43], v59 offset:16384
	ds_read_b64 v[50:51], v60 offset:24576
	v_mul_f32_e32 v20, 0x38800000, v20
	v_cos_f32_e32 v40, v20
	v_sin_f32_e32 v52, v20
	s_waitcnt lgkmcnt(3)
	v_pk_add_f32 v[34:35], v[2:3], 0 op_sel_hi:[1,0]
	ds_read_b64 v[48:49], v61 offset:32768
	ds_read_b64 v[36:37], v62 offset:40960
	ds_read_b64 v[46:47], v63 offset:49152
	ds_read_b64 v[38:39], v64 offset:57344
	v_pk_mul_f32 v[30:31], v[2:3], v[52:53] op_sel:[1,0] op_sel_hi:[0,0]
	v_mov_b32_e32 v53, v40
	v_pk_fma_f32 v[20:21], v[2:3], v[40:41], v[30:31]
	v_pk_fma_f32 v[2:3], v[2:3], v[40:41], v[30:31] op_sel_hi:[1,0,1] neg_lo:[0,0,1] neg_hi:[0,0,1]
	v_pk_mul_f32 v[54:55], v[52:53], s[94:95] op_sel_hi:[1,0]
	s_mov_b32 s27, s14
	v_fma_f32 v2, v52, s88, -v55
	s_waitcnt lgkmcnt(5)
	v_pk_mul_f32 v[44:45], v[42:43], v[2:3] op_sel:[1,0] op_sel_hi:[0,0]
	v_pk_add_f32 v[66:67], v[54:55], v[54:55] op_sel:[1,0] op_sel_hi:[1,0] neg_lo:[0,1] neg_hi:[0,1]
	v_mov_b32_e32 v21, v3
	v_pk_add_f32 v[30:31], v[42:43], 0 op_sel_hi:[1,0]
	v_pk_fma_f32 v[2:3], v[42:43], v[66:67], v[44:45] neg_lo:[0,0,1]
	v_pk_mul_f32 v[66:67], v[52:53], s[26:27]
	v_pk_mul_f32 v[42:43], v[52:53], s[14:15]
	v_pk_add_f32 v[70:71], v[66:67], v[66:67] op_sel:[0,1] op_sel_hi:[0,1] neg_lo:[0,1] neg_hi:[0,1]
	s_waitcnt lgkmcnt(4)
	v_pk_mul_f32 v[70:71], v[50:51], v[70:71] op_sel:[1,0] op_sel_hi:[0,1]
	v_pk_add_f32 v[72:73], v[42:43], v[42:43] op_sel:[1,0] op_sel_hi:[1,0] neg_lo:[0,1] neg_hi:[0,1]
	v_pk_add_f32 v[68:69], v[50:51], 0 op_sel_hi:[1,0]
	v_pk_fma_f32 v[74:75], v[50:51], v[72:73], v[70:71] neg_lo:[0,0,1] neg_hi:[0,0,1]
	v_pk_fma_f32 v[50:51], v[50:51], v[72:73], v[70:71]
	v_fma_f32 v66, v52, s39, -v40
	v_fma_f32 v50, v40, 0, -v52
	s_waitcnt lgkmcnt(3)
	v_pk_mul_f32 v[72:73], v[48:49], v[66:67] op_sel:[1,0] op_sel_hi:[0,0]
	v_fma_f32 v66, v40, s88, -v54
	v_pk_add_f32 v[54:55], v[54:55], v[54:55] op_sel:[0,1] op_sel_hi:[0,1] neg_lo:[0,1] neg_hi:[0,1]
	v_pk_add_f32 v[70:71], v[48:49], 0 op_sel_hi:[1,0]
	v_pk_fma_f32 v[76:77], v[48:49], v[50:51], v[72:73] neg_lo:[0,0,1] neg_hi:[0,0,1]
	v_pk_fma_f32 v[48:49], v[48:49], v[50:51], v[72:73] op_sel_hi:[1,0,1]
	s_waitcnt lgkmcnt(1)
	v_pk_mul_f32 v[54:55], v[54:55], v[46:47] op_sel:[0,1] op_sel_hi:[1,0]
	v_mov_b32_e32 v41, v52
	s_mov_b32 s81, s15
	v_fma_f32 v44, v52, s80, -v43
	v_fma_f32 v48, v40, s26, -v42
	v_pk_add_f32 v[72:73], v[46:47], 0 op_sel_hi:[1,0]
	v_pk_fma_f32 v[78:79], v[66:67], v[46:47], v[54:55] neg_lo:[0,0,1] neg_hi:[0,0,1]
	v_pk_fma_f32 v[46:47], v[66:67], v[46:47], v[54:55] op_sel_hi:[0,1,1]
	v_pk_mul_f32 v[40:41], v[40:41], s[80:81]
	v_pk_mul_f32 v[44:45], v[22:23], v[44:45] op_sel:[1,0] op_sel_hi:[0,0]
	v_sub_f32_e32 v46, v67, v41
	v_pk_add_f32 v[32:33], v[22:23], 0 op_sel_hi:[1,0]
	v_pk_fma_f32 v[52:53], v[22:23], v[46:47], v[44:45] op_sel_hi:[1,0,1] neg_lo:[0,0,1] neg_hi:[0,0,1]
	v_pk_fma_f32 v[22:23], v[22:23], v[46:47], v[44:45] op_sel_hi:[1,0,1]
	v_mov_b32_e32 v75, v51
	v_sub_f32_e32 v22, v41, v67
	v_mov_b32_e32 v53, v23
	v_pk_mul_f32 v[22:23], v[22:23], v[36:37] op_sel:[0,1] op_sel_hi:[0,0]
	v_pk_add_f32 v[50:51], v[36:37], 0 op_sel_hi:[1,0]
	v_pk_fma_f32 v[44:45], v[48:49], v[36:37], v[22:23] op_sel_hi:[0,1,1] neg_lo:[0,0,1]
	v_pk_add_f32 v[36:37], v[42:43], v[42:43] op_sel:[0,1] op_sel_hi:[0,1] neg_lo:[0,1] neg_hi:[0,1]
	s_waitcnt lgkmcnt(0)
	v_pk_mul_f32 v[36:37], v[36:37], v[38:39] op_sel:[0,1] op_sel_hi:[1,0]
	v_pk_add_f32 v[40:41], v[40:41], v[40:41] op_sel:[0,1] op_sel_hi:[0,1] neg_lo:[0,1] neg_hi:[0,1]
	v_pk_fma_f32 v[42:43], v[40:41], v[38:39], v[36:37] neg_lo:[0,0,1] neg_hi:[0,0,1]
	v_pk_fma_f32 v[36:37], v[40:41], v[38:39], v[36:37]
	v_lshlrev_b32_e32 v36, 1, v65
	v_cvt_f32_u32_e32 v36, v36
	v_mov_b32_e32 v43, v37
	v_pk_add_f32 v[22:23], v[38:39], 0 op_sel_hi:[1,0]
	v_pk_add_f32 v[40:41], v[34:35], v[70:71]
	v_mul_f32_e32 v37, 0x38800000, v36
	v_sin_f32_e32 v38, v37
	v_cos_f32_e32 v36, v37
	v_pk_add_f32 v[34:35], v[34:35], v[70:71] neg_lo:[0,1] neg_hi:[0,1]
	v_mov_b32_e32 v79, v47
	v_pk_mul_f32 v[46:47], v[38:39], v[34:35] op_sel_hi:[0,1]
	v_mov_b32_e32 v77, v49
	v_pk_fma_f32 v[48:49], v[36:37], v[34:35], v[46:47] op_sel:[0,0,1] op_sel_hi:[0,1,0] neg_hi:[0,0,1]
	v_mov_b32_e32 v39, v36
	v_pk_mul_f32 v[34:35], v[38:39], s[94:95] op_sel_hi:[1,0]
	v_pk_add_f32 v[54:55], v[32:33], v[50:51]
	v_fma_f32 v46, v38, s88, -v35
	v_pk_add_f32 v[32:33], v[32:33], v[50:51] neg_lo:[0,1] neg_hi:[0,1]
	v_pk_add_f32 v[66:67], v[34:35], v[34:35] op_sel:[1,0] op_sel_hi:[1,0] neg_lo:[0,1] neg_hi:[0,1]
	v_pk_mul_f32 v[50:51], v[46:47], v[32:33] op_sel_hi:[0,1]
	v_pk_fma_f32 v[70:71], v[66:67], v[32:33], v[50:51] op_sel:[0,0,1] op_sel_hi:[1,1,0] neg_lo:[0,0,1] neg_hi:[0,0,1]
	v_pk_fma_f32 v[32:33], v[66:67], v[32:33], v[50:51] op_sel:[0,0,1] op_sel_hi:[1,1,0]
	v_fma_f32 v50, v38, s39, -v36
	v_pk_add_f32 v[80:81], v[30:31], v[72:73]
	v_pk_add_f32 v[30:31], v[30:31], v[72:73] neg_lo:[0,1] neg_hi:[0,1]
	v_fma_f32 v32, v36, 0, -v38
	v_pk_mul_f32 v[72:73], v[50:51], v[30:31] op_sel_hi:[0,1]
	v_pk_fma_f32 v[82:83], v[32:33], v[30:31], v[72:73] op_sel:[0,0,1] op_sel_hi:[1,1,0] neg_lo:[0,0,1] neg_hi:[0,0,1]
	v_pk_fma_f32 v[30:31], v[32:33], v[30:31], v[72:73] op_sel:[0,0,1] op_sel_hi:[0,1,0]
	v_fma_f32 v30, v36, s88, -v34
	v_pk_add_f32 v[72:73], v[68:69], v[22:23]
	v_pk_add_f32 v[22:23], v[68:69], v[22:23] neg_lo:[0,1] neg_hi:[0,1]
	v_pk_add_f32 v[34:35], v[34:35], v[34:35] op_sel:[0,1] op_sel_hi:[0,1] neg_lo:[0,1] neg_hi:[0,1]
	v_pk_mul_f32 v[68:69], v[34:35], v[22:23]
	v_mov_b32_e32 v71, v33
	v_pk_fma_f32 v[114:115], v[30:31], v[22:23], v[68:69] op_sel:[0,0,1] op_sel_hi:[0,1,0] neg_lo:[0,0,1]
	v_pk_add_f32 v[22:23], v[20:21], v[76:77]
	v_pk_add_f32 v[20:21], v[20:21], v[76:77] neg_lo:[0,1] neg_hi:[0,1]
	v_mov_b32_e32 v83, v31
	v_pk_mul_f32 v[38:39], v[38:39], v[20:21] op_sel_hi:[0,1]
	v_pk_fma_f32 v[68:69], v[36:37], v[20:21], v[38:39] op_sel:[0,0,1] op_sel_hi:[0,1,0] neg_hi:[0,0,1]
	v_pk_add_f32 v[36:37], v[52:53], v[44:45] neg_lo:[0,1] neg_hi:[0,1]
	v_pk_mul_f32 v[38:39], v[46:47], v[36:37] op_sel_hi:[0,1]
	v_pk_add_f32 v[20:21], v[52:53], v[44:45]
	v_pk_fma_f32 v[44:45], v[66:67], v[36:37], v[38:39] op_sel:[0,0,1] op_sel_hi:[1,1,0] neg_lo:[0,0,1]
	v_pk_add_f32 v[52:53], v[54:55], v[72:73]
	v_pk_add_f32 v[36:37], v[2:3], v[78:79]
	v_pk_add_f32 v[2:3], v[2:3], v[78:79] neg_lo:[0,1] neg_hi:[0,1]
	v_pk_add_f32 v[54:55], v[54:55], v[72:73] neg_lo:[0,1] neg_hi:[0,1]
	v_pk_mul_f32 v[38:39], v[50:51], v[2:3] op_sel_hi:[0,1]
	v_pk_fma_f32 v[46:47], v[32:33], v[2:3], v[38:39] op_sel:[0,0,1] op_sel_hi:[0,1,0] neg_lo:[0,0,1]
	v_pk_add_f32 v[32:33], v[74:75], v[42:43] neg_lo:[0,1] neg_hi:[0,1]
	v_pk_mul_f32 v[34:35], v[34:35], v[32:33]
	v_pk_add_f32 v[2:3], v[74:75], v[42:43]
	v_pk_fma_f32 v[38:39], v[30:31], v[32:33], v[34:35] op_sel:[0,0,1] op_sel_hi:[1,1,0] neg_lo:[0,0,1] neg_hi:[0,0,1]
	v_pk_fma_f32 v[30:31], v[30:31], v[32:33], v[34:35] op_sel:[0,0,1] op_sel_hi:[0,1,0]
	v_lshlrev_b32_e32 v30, 2, v65
	v_cvt_f32_u32_e32 v30, v30
	v_mov_b32_e32 v39, v31
	v_pk_add_f32 v[34:35], v[40:41], v[80:81]
	v_pk_add_f32 v[40:41], v[40:41], v[80:81] neg_lo:[0,1] neg_hi:[0,1]
	v_mul_f32_e32 v31, 0x38800000, v30
	v_sin_f32_e32 v32, v31
	v_cos_f32_e32 v30, v31
	v_cmp_lt_i32_e32 vcc, s35, v25
	v_add_u32_e32 v0, 0x2000, v0
	v_pk_mul_f32 v[42:43], v[32:33], v[40:41] op_sel_hi:[0,1]
	v_pk_fma_f32 v[50:51], v[30:31], v[40:41], v[42:43] op_sel:[0,0,1] op_sel_hi:[1,1,0]
	v_pk_fma_f32 v[40:41], v[30:31], v[40:41], v[42:43] op_sel:[0,0,1] op_sel_hi:[0,1,0] neg_lo:[0,0,1] neg_hi:[0,0,1]
	v_fma_f32 v42, v32, s39, -v30
	v_fma_f32 v40, v30, 0, -v32
	v_pk_mul_f32 v[66:67], v[42:43], v[54:55] op_sel_hi:[0,1]
	v_pk_fma_f32 v[72:73], v[40:41], v[54:55], v[66:67] op_sel:[0,0,1] op_sel_hi:[0,1,0] neg_lo:[0,0,1]
	v_pk_add_f32 v[54:55], v[48:49], v[82:83]
	v_pk_add_f32 v[48:49], v[48:49], v[82:83] neg_lo:[0,1] neg_hi:[0,1]
	v_mov_b32_e32 v51, v41
	v_pk_mul_f32 v[66:67], v[32:33], v[48:49] op_sel_hi:[0,1]
	v_pk_fma_f32 v[74:75], v[30:31], v[48:49], v[66:67] op_sel:[0,0,1] op_sel_hi:[0,1,0] neg_hi:[0,0,1]
	v_pk_add_f32 v[66:67], v[70:71], v[114:115] neg_lo:[0,1] neg_hi:[0,1]
	v_pk_add_f32 v[48:49], v[70:71], v[114:115]
	v_pk_mul_f32 v[70:71], v[42:43], v[66:67] op_sel_hi:[0,1]
	v_pk_fma_f32 v[76:77], v[40:41], v[66:67], v[70:71] op_sel:[0,0,1] op_sel_hi:[0,1,0] neg_lo:[0,0,1]
	v_pk_add_f32 v[66:67], v[22:23], v[36:37]
	v_pk_add_f32 v[22:23], v[22:23], v[36:37] neg_lo:[0,1] neg_hi:[0,1]
	s_or_b64 s[12:13], vcc, s[12:13]
	v_pk_mul_f32 v[36:37], v[32:33], v[22:23] op_sel_hi:[0,1]
	v_pk_fma_f32 v[70:71], v[30:31], v[22:23], v[36:37] op_sel:[0,0,1] op_sel_hi:[0,1,0] neg_hi:[0,0,1]
	v_pk_add_f32 v[22:23], v[20:21], v[2:3]
	v_pk_add_f32 v[2:3], v[20:21], v[2:3] neg_lo:[0,1] neg_hi:[0,1]
	s_nop 0
	v_pk_mul_f32 v[20:21], v[42:43], v[2:3] op_sel_hi:[0,1]
	v_pk_fma_f32 v[36:37], v[40:41], v[2:3], v[20:21] op_sel:[0,0,1] op_sel_hi:[0,1,0] neg_lo:[0,0,1]
	v_pk_add_f32 v[20:21], v[68:69], v[46:47] neg_lo:[0,1] neg_hi:[0,1]
	v_pk_mul_f32 v[32:33], v[32:33], v[20:21] op_sel_hi:[0,1]
	v_pk_add_f32 v[2:3], v[68:69], v[46:47]
	v_pk_fma_f32 v[46:47], v[30:31], v[20:21], v[32:33] op_sel:[0,0,1] op_sel_hi:[0,1,0] neg_hi:[0,0,1]
	v_pk_add_f32 v[30:31], v[44:45], v[38:39] neg_lo:[0,1] neg_hi:[0,1]
	v_pk_mul_f32 v[32:33], v[42:43], v[30:31] op_sel_hi:[0,1]
	v_pk_add_f32 v[20:21], v[44:45], v[38:39]
	v_pk_fma_f32 v[38:39], v[40:41], v[30:31], v[32:33] op_sel:[0,0,1] op_sel_hi:[1,1,0] neg_lo:[0,0,1] neg_hi:[0,0,1]
	v_pk_fma_f32 v[30:31], v[40:41], v[30:31], v[32:33] op_sel:[0,0,1] op_sel_hi:[0,1,0]
	v_lshlrev_b32_e32 v30, 3, v65
	v_cvt_f32_u32_e32 v30, v30
	v_mov_b32_e32 v39, v31
	v_pk_add_f32 v[40:41], v[34:35], v[52:53]
	v_pk_add_f32 v[34:35], v[34:35], v[52:53] neg_lo:[0,1] neg_hi:[0,1]
	v_mul_f32_e32 v31, 0x38800000, v30
	v_sin_f32_e32 v32, v31
	v_cos_f32_e32 v30, v31
	v_pk_mul_f32 v[42:43], v[32:33], v[34:35] op_sel_hi:[0,1]
	v_pk_fma_f32 v[44:45], v[30:31], v[34:35], v[42:43] op_sel:[0,0,1] op_sel_hi:[0,1,0] neg_hi:[0,0,1]
	v_pk_add_f32 v[42:43], v[50:51], v[72:73] neg_lo:[0,1] neg_hi:[0,1]
	v_pk_add_f32 v[34:35], v[50:51], v[72:73]
	v_pk_mul_f32 v[50:51], v[32:33], v[42:43] op_sel_hi:[0,1]
	v_pk_fma_f32 v[52:53], v[30:31], v[42:43], v[50:51] op_sel:[0,0,1] op_sel_hi:[0,1,0] neg_hi:[0,0,1]
	v_pk_add_f32 v[42:43], v[54:55], v[48:49]
	v_pk_add_f32 v[48:49], v[54:55], v[48:49] neg_lo:[0,1] neg_hi:[0,1]
	s_nop 0
	v_pk_mul_f32 v[50:51], v[32:33], v[48:49] op_sel_hi:[0,1]
	v_pk_fma_f32 v[54:55], v[30:31], v[48:49], v[50:51] op_sel:[0,0,1] op_sel_hi:[0,1,0] neg_hi:[0,0,1]
	v_pk_add_f32 v[50:51], v[74:75], v[76:77] neg_lo:[0,1] neg_hi:[0,1]
	v_pk_mul_f32 v[68:69], v[32:33], v[50:51] op_sel_hi:[0,1]
	v_pk_fma_f32 v[72:73], v[30:31], v[50:51], v[68:69] op_sel:[0,0,1] op_sel_hi:[0,1,0] neg_hi:[0,0,1]
	v_pk_add_f32 v[50:51], v[66:67], v[22:23]
	v_pk_add_f32 v[22:23], v[66:67], v[22:23] neg_lo:[0,1] neg_hi:[0,1]
	v_pk_add_f32 v[48:49], v[74:75], v[76:77]
	v_pk_mul_f32 v[66:67], v[32:33], v[22:23] op_sel_hi:[0,1]
	v_pk_fma_f32 v[68:69], v[30:31], v[22:23], v[66:67] op_sel:[0,0,1] op_sel_hi:[0,1,0] neg_hi:[0,0,1]
	v_pk_add_f32 v[22:23], v[70:71], v[36:37]
	v_pk_add_f32 v[36:37], v[70:71], v[36:37] neg_lo:[0,1] neg_hi:[0,1]
	ds_write_b64 v57, v[40:41]
	ds_write_b64 v58, v[44:45] offset:8192
	ds_write_b64 v59, v[34:35] offset:16384
	ds_write_b64 v60, v[52:53] offset:24576
	ds_write_b64 v61, v[42:43] offset:32768
	ds_write_b64 v62, v[54:55] offset:40960
	ds_write_b64 v63, v[48:49] offset:49152
	ds_write_b64 v64, v[72:73] offset:57344
	v_pk_mul_f32 v[66:67], v[32:33], v[36:37] op_sel_hi:[0,1]
	v_pk_fma_f32 v[70:71], v[30:31], v[36:37], v[66:67] op_sel:[0,0,1] op_sel_hi:[0,1,0] neg_hi:[0,0,1]
	v_pk_add_f32 v[36:37], v[2:3], v[20:21] neg_lo:[0,1] neg_hi:[0,1]
	v_pk_add_f32 v[2:3], v[2:3], v[20:21]
	v_pk_mul_f32 v[66:67], v[32:33], v[36:37] op_sel_hi:[0,1]
	v_pk_fma_f32 v[74:75], v[30:31], v[36:37], v[66:67] op_sel:[0,0,1] op_sel_hi:[0,1,0] neg_hi:[0,0,1]
	v_pk_add_f32 v[36:37], v[46:47], v[38:39] neg_lo:[0,1] neg_hi:[0,1]
	v_pk_add_f32 v[20:21], v[46:47], v[38:39]
	v_pk_mul_f32 v[32:33], v[32:33], v[36:37] op_sel_hi:[0,1]
	v_pk_fma_f32 v[38:39], v[30:31], v[36:37], v[32:33] op_sel:[0,0,1] op_sel_hi:[1,1,0]
	v_pk_fma_f32 v[30:31], v[30:31], v[36:37], v[32:33] op_sel:[0,0,1] op_sel_hi:[0,1,0] neg_lo:[0,0,1] neg_hi:[0,0,1]
	v_or_b32_e32 v30, 0x2000, v56
	v_mov_b32_e32 v39, v31
	v_ashrrev_i32_e32 v31, 5, v30
	v_lshlrev_b32_e32 v30, 3, v30
	v_lshlrev_b32_e32 v31, 3, v31
	v_add3_u32 v30, 0, v30, v31
	ds_write_b64 v30, v[50:51]
	v_or_b32_e32 v30, 0x2400, v56
	v_ashrrev_i32_e32 v31, 5, v30
	v_lshlrev_b32_e32 v30, 3, v30
	v_lshlrev_b32_e32 v31, 3, v31
	v_add3_u32 v30, 0, v30, v31
	ds_write_b64 v30, v[68:69]
	v_or_b32_e32 v30, 0x2800, v56
	v_ashrrev_i32_e32 v31, 5, v30
	v_lshlrev_b32_e32 v30, 3, v30
	v_lshlrev_b32_e32 v31, 3, v31
	v_add3_u32 v30, 0, v30, v31
	ds_write_b64 v30, v[22:23]
	v_or_b32_e32 v22, 0x2c00, v56
	v_ashrrev_i32_e32 v23, 5, v22
	v_lshlrev_b32_e32 v22, 3, v22
	v_lshlrev_b32_e32 v23, 3, v23
	v_add3_u32 v22, 0, v22, v23
	ds_write_b64 v22, v[70:71]
	v_or_b32_e32 v22, 0x3000, v56
	v_ashrrev_i32_e32 v23, 5, v22
	v_lshlrev_b32_e32 v22, 3, v22
	v_lshlrev_b32_e32 v23, 3, v23
	v_add3_u32 v22, 0, v22, v23
	ds_write_b64 v22, v[2:3]
	v_or_b32_e32 v2, 0x3400, v56
	v_ashrrev_i32_e32 v3, 5, v2
	v_lshlrev_b32_e32 v2, 3, v2
	v_lshlrev_b32_e32 v3, 3, v3
	v_add3_u32 v2, 0, v2, v3
	ds_write_b64 v2, v[74:75]
	v_or_b32_e32 v2, 0x3800, v56
	v_ashrrev_i32_e32 v3, 5, v2
	v_lshlrev_b32_e32 v2, 3, v2
	v_lshlrev_b32_e32 v3, 3, v3
	v_add3_u32 v2, 0, v2, v3
	ds_write_b64 v2, v[20:21]
	v_or_b32_e32 v2, 0x3c00, v56
	v_ashrrev_i32_e32 v3, 5, v2
	v_lshlrev_b32_e32 v2, 3, v2
	v_lshlrev_b32_e32 v3, 3, v3
	v_add3_u32 v2, 0, v2, v3
	ds_write_b64 v2, v[38:39]
	v_add_u32_e32 v2, 0x200, v25
	v_mov_b32_e32 v25, v2
	s_andn2_b64 exec, exec, s[12:13]
	s_cbranch_execnz .LBB0_663

.LBB0_666:
	v_and_or_b32 v140, v111, s42, v0
	v_or_b32_e32 v128, 0x200, v140
	v_ashrrev_i32_e32 v114, 5, v140
	v_lshl_add_u32 v141, v140, 3, 0
	v_ashrrev_i32_e32 v128, 5, v128
	v_lshl_add_u32 v152, v114, 3, v141
	v_or_b32_e32 v114, 64, v140
	v_or_b32_e32 v116, 0x80, v140
	v_or_b32_e32 v118, 0xc0, v140
	v_or_b32_e32 v120, 0x100, v140
	v_or_b32_e32 v122, 0x140, v140
	v_or_b32_e32 v124, 0x180, v140
	v_or_b32_e32 v126, 0x1c0, v140
	v_lshl_add_u32 v160, v128, 3, v141
	v_or_b32_e32 v128, 0x240, v140
	v_or_b32_e32 v130, 0x280, v140
	v_or_b32_e32 v132, 0x2c0, v140
	v_or_b32_e32 v134, 0x300, v140
	v_or_b32_e32 v136, 0x340, v140
	v_or_b32_e32 v138, 0x380, v140
	v_or_b32_e32 v140, 0x3c0, v140
	v_ashrrev_i32_e32 v114, 5, v114
	v_ashrrev_i32_e32 v116, 5, v116
	v_ashrrev_i32_e32 v118, 5, v118
	v_ashrrev_i32_e32 v120, 5, v120
	v_ashrrev_i32_e32 v122, 5, v122
	v_ashrrev_i32_e32 v124, 5, v124
	v_ashrrev_i32_e32 v126, 5, v126
	v_ashrrev_i32_e32 v128, 5, v128
	v_ashrrev_i32_e32 v130, 5, v130
	v_ashrrev_i32_e32 v132, 5, v132
	v_ashrrev_i32_e32 v134, 5, v134
	v_ashrrev_i32_e32 v136, 5, v136
	v_ashrrev_i32_e32 v138, 5, v138
	v_ashrrev_i32_e32 v140, 5, v140
	v_lshl_add_u32 v153, v114, 3, v141
	v_lshl_add_u32 v154, v116, 3, v141
	v_lshl_add_u32 v155, v118, 3, v141
	v_lshl_add_u32 v156, v120, 3, v141
	v_lshl_add_u32 v157, v122, 3, v141
	v_lshl_add_u32 v158, v124, 3, v141
	v_lshl_add_u32 v159, v126, 3, v141
	v_lshl_add_u32 v161, v128, 3, v141
	v_lshl_add_u32 v162, v130, 3, v141
	v_lshl_add_u32 v163, v132, 3, v141
	v_lshl_add_u32 v164, v134, 3, v141
	v_lshl_add_u32 v165, v136, 3, v141
	v_lshl_add_u32 v166, v138, 3, v141
	v_lshl_add_u32 v167, v140, 3, v141
	ds_read_b64 v[114:115], v153 offset:512
	ds_read_b64 v[116:117], v154 offset:1024
	ds_read_b64 v[118:119], v155 offset:1536
	ds_read_b64 v[120:121], v156 offset:2048
	ds_read_b64 v[122:123], v157 offset:2560
	ds_read_b64 v[124:125], v158 offset:3072
	ds_read_b64 v[126:127], v159 offset:3584
	ds_read_b64 v[128:129], v161 offset:4608
	ds_read_b64 v[130:131], v162 offset:5120
	ds_read_b64 v[132:133], v163 offset:5632
	ds_read_b64 v[134:135], v164 offset:6144
	ds_read_b64 v[136:137], v165 offset:6656
	ds_read_b64 v[138:139], v166 offset:7168
	ds_read_b64 v[140:141], v167 offset:7680
	ds_read_b64 v[142:143], v160 offset:4096
	ds_read_b64 v[144:145], v152
	v_add_u32_e32 v25, 0x200, v25
	v_cmp_lt_i32_e32 vcc, s35, v25
	v_add_u32_e32 v111, 0x2000, v111
	s_or_b64 s[12:13], vcc, s[12:13]
	s_waitcnt lgkmcnt(0)
	v_pk_add_f32 v[146:147], v[142:143], v[144:145]
	v_pk_add_f32 v[142:143], v[144:145], v[142:143] neg_lo:[0,1] neg_hi:[0,1]
	s_nop 0
	v_pk_mul_f32 v[144:145], v[20:21], v[142:143] op_sel:[0,1] op_sel_hi:[1,0]
	s_nop 0
	v_pk_fma_f32 v[148:149], v[2:3], v[142:143], v[144:145] neg_hi:[0,0,1]
	v_pk_add_f32 v[142:143], v[114:115], v[128:129]
	v_pk_add_f32 v[114:115], v[114:115], v[128:129] neg_lo:[0,1] neg_hi:[0,1]
	s_nop 0
	v_pk_mul_f32 v[128:129], v[40:41], v[114:115] op_sel:[0,1] op_sel_hi:[1,0]
	s_nop 0
	v_pk_fma_f32 v[144:145], v[38:39], v[114:115], v[128:129] neg_lo:[0,0,1]
	v_pk_add_f32 v[114:115], v[116:117], v[130:131]
	v_pk_add_f32 v[116:117], v[116:117], v[130:131] neg_lo:[0,1] neg_hi:[0,1]
	s_nop 0
	v_pk_mul_f32 v[128:129], v[44:45], v[116:117] op_sel:[0,1] op_sel_hi:[1,0]
	s_nop 0
	v_pk_fma_f32 v[130:131], v[42:43], v[116:117], v[128:129] neg_lo:[0,0,1]
	v_pk_add_f32 v[116:117], v[118:119], v[132:133]
	v_pk_add_f32 v[118:119], v[118:119], v[132:133] neg_lo:[0,1] neg_hi:[0,1]
	s_nop 0
	v_pk_mul_f32 v[128:129], v[48:49], v[118:119] op_sel:[0,1] op_sel_hi:[1,0]
	s_nop 0
	v_pk_fma_f32 v[132:133], v[32:33], v[118:119], v[128:129] neg_lo:[0,0,1]
	v_pk_add_f32 v[118:119], v[120:121], v[134:135]
	v_pk_add_f32 v[120:121], v[120:121], v[134:135] neg_lo:[0,1] neg_hi:[0,1]
	s_nop 0
	v_pk_mul_f32 v[128:129], v[52:53], v[120:121] op_sel:[0,1] op_sel_hi:[1,0]
	s_nop 0
	v_pk_fma_f32 v[134:135], v[50:51], v[120:121], v[128:129] neg_lo:[0,0,1]
	v_pk_add_f32 v[120:121], v[122:123], v[136:137]
	v_pk_add_f32 v[122:123], v[122:123], v[136:137] neg_lo:[0,1] neg_hi:[0,1]
	s_nop 0
	v_pk_mul_f32 v[128:129], v[22:23], v[122:123] op_sel:[0,1] op_sel_hi:[1,0]
	s_nop 0
	v_pk_fma_f32 v[136:137], v[46:47], v[122:123], v[128:129] neg_lo:[0,0,1]
	v_pk_add_f32 v[122:123], v[124:125], v[138:139]
	v_pk_add_f32 v[124:125], v[124:125], v[138:139] neg_lo:[0,1] neg_hi:[0,1]
	s_nop 0
	v_pk_mul_f32 v[128:129], v[34:35], v[124:125] op_sel:[0,1] op_sel_hi:[1,0]
	s_nop 0
	v_pk_fma_f32 v[138:139], v[36:37], v[124:125], v[128:129] neg_lo:[0,0,1]
	v_pk_add_f32 v[124:125], v[126:127], v[140:141]
	v_pk_add_f32 v[126:127], v[126:127], v[140:141] neg_lo:[0,1] neg_hi:[0,1]
	s_nop 0
	v_pk_mul_f32 v[128:129], v[58:59], v[126:127] op_sel:[0,1] op_sel_hi:[1,0]
	s_nop 0
	v_pk_fma_f32 v[140:141], v[30:31], v[126:127], v[128:129] neg_lo:[0,0,1]
	v_pk_add_f32 v[126:127], v[118:119], v[146:147]
	v_pk_add_f32 v[118:119], v[146:147], v[118:119] neg_lo:[0,1] neg_hi:[0,1]
	s_nop 0
	v_pk_mul_f32 v[128:129], v[56:57], v[118:119]
	s_nop 0
	v_pk_fma_f32 v[146:147], v[54:55], v[118:119], v[128:129] op_sel:[0,0,1] op_sel_hi:[1,1,0] neg_hi:[0,0,1]
	v_pk_add_f32 v[118:119], v[142:143], v[120:121]
	v_pk_add_f32 v[120:121], v[142:143], v[120:121] neg_lo:[0,1] neg_hi:[0,1]
	s_nop 0
	v_pk_mul_f32 v[128:129], v[66:67], v[120:121]
	s_nop 0
	v_pk_fma_f32 v[142:143], v[64:65], v[120:121], v[128:129] op_sel:[0,0,1] op_sel_hi:[1,1,0] neg_lo:[0,0,1]
	v_pk_add_f32 v[120:121], v[114:115], v[122:123]
	v_pk_add_f32 v[114:115], v[114:115], v[122:123] neg_lo:[0,1] neg_hi:[0,1]
	s_nop 0
	v_pk_mul_f32 v[122:123], v[70:71], v[114:115]
	s_nop 0
	v_pk_fma_f32 v[128:129], v[68:69], v[114:115], v[122:123] op_sel:[0,0,1] op_sel_hi:[1,1,0] neg_lo:[0,0,1]
	v_pk_add_f32 v[114:115], v[116:117], v[124:125]
	v_pk_add_f32 v[116:117], v[116:117], v[124:125] neg_lo:[0,1] neg_hi:[0,1]
	s_nop 0
	v_pk_mul_f32 v[122:123], v[60:61], v[116:117]
	s_nop 0
	v_pk_fma_f32 v[124:125], v[62:63], v[116:117], v[122:123] op_sel:[0,0,1] op_sel_hi:[1,1,0] neg_lo:[0,0,1]
	v_pk_add_f32 v[122:123], v[148:149], v[134:135] neg_lo:[0,1] neg_hi:[0,1]
	v_pk_add_f32 v[116:117], v[134:135], v[148:149]
	v_pk_mul_f32 v[134:135], v[56:57], v[122:123]
	s_nop 0
	v_pk_fma_f32 v[148:149], v[54:55], v[122:123], v[134:135] op_sel:[0,0,1] op_sel_hi:[1,1,0] neg_hi:[0,0,1]
	v_pk_add_f32 v[134:135], v[144:145], v[136:137] neg_lo:[0,1] neg_hi:[0,1]
	v_pk_add_f32 v[122:123], v[144:145], v[136:137]
	v_pk_mul_f32 v[136:137], v[66:67], v[134:135]
	s_nop 0
	v_pk_fma_f32 v[144:145], v[64:65], v[134:135], v[136:137] op_sel:[0,0,1] op_sel_hi:[1,1,0] neg_lo:[0,0,1]
	v_pk_add_f32 v[134:135], v[130:131], v[138:139]
	v_pk_add_f32 v[130:131], v[130:131], v[138:139] neg_lo:[0,1] neg_hi:[0,1]
	s_nop 0
	v_pk_mul_f32 v[136:137], v[70:71], v[130:131]
	s_nop 0
	v_pk_fma_f32 v[138:139], v[68:69], v[130:131], v[136:137] op_sel:[0,0,1] op_sel_hi:[1,1,0] neg_lo:[0,0,1]
	v_pk_add_f32 v[130:131], v[132:133], v[140:141]
	v_pk_add_f32 v[132:133], v[132:133], v[140:141] neg_lo:[0,1] neg_hi:[0,1]
	s_nop 0
	v_pk_mul_f32 v[136:137], v[60:61], v[132:133]
	s_nop 0
	v_pk_fma_f32 v[140:141], v[62:63], v[132:133], v[136:137] op_sel:[0,0,1] op_sel_hi:[1,1,0] neg_lo:[0,0,1]
	v_pk_add_f32 v[132:133], v[120:121], v[126:127]
	v_pk_add_f32 v[120:121], v[126:127], v[120:121] neg_lo:[0,1] neg_hi:[0,1]
	s_nop 0
	v_pk_mul_f32 v[126:127], v[74:75], v[120:121]
	s_nop 0
	v_pk_fma_f32 v[136:137], v[72:73], v[120:121], v[126:127] op_sel:[0,0,1] op_sel_hi:[1,1,0] neg_hi:[0,0,1]
	v_pk_add_f32 v[120:121], v[118:119], v[114:115]
	v_pk_add_f32 v[114:115], v[118:119], v[114:115] neg_lo:[0,1] neg_hi:[0,1]
	s_nop 0
	v_pk_mul_f32 v[118:119], v[78:79], v[114:115]
	s_nop 0
	v_pk_fma_f32 v[126:127], v[76:77], v[114:115], v[118:119] op_sel:[0,0,1] op_sel_hi:[1,1,0] neg_lo:[0,0,1]
	v_pk_add_f32 v[118:119], v[146:147], v[128:129] neg_lo:[0,1] neg_hi:[0,1]
	v_pk_add_f32 v[114:115], v[128:129], v[146:147]
	v_pk_mul_f32 v[128:129], v[74:75], v[118:119]
	s_nop 0
	v_pk_fma_f32 v[146:147], v[72:73], v[118:119], v[128:129] op_sel:[0,0,1] op_sel_hi:[1,1,0] neg_hi:[0,0,1]
	v_pk_add_f32 v[118:119], v[142:143], v[124:125]
	v_pk_add_f32 v[124:125], v[142:143], v[124:125] neg_lo:[0,1] neg_hi:[0,1]
	s_nop 0
	v_pk_mul_f32 v[128:129], v[78:79], v[124:125]
	s_nop 0
	v_pk_fma_f32 v[142:143], v[76:77], v[124:125], v[128:129] op_sel:[0,0,1] op_sel_hi:[1,1,0] neg_lo:[0,0,1]
	v_pk_add_f32 v[124:125], v[134:135], v[116:117]
	v_pk_add_f32 v[116:117], v[116:117], v[134:135] neg_lo:[0,1] neg_hi:[0,1]
	s_nop 0
	v_pk_mul_f32 v[128:129], v[74:75], v[116:117]
	s_nop 0
	v_pk_fma_f32 v[134:135], v[72:73], v[116:117], v[128:129] op_sel:[0,0,1] op_sel_hi:[1,1,0] neg_hi:[0,0,1]
	v_pk_add_f32 v[116:117], v[122:123], v[130:131]
	v_pk_add_f32 v[122:123], v[122:123], v[130:131] neg_lo:[0,1] neg_hi:[0,1]
	s_nop 0
	v_pk_mul_f32 v[128:129], v[78:79], v[122:123]
	s_nop 0
	v_pk_fma_f32 v[130:131], v[76:77], v[122:123], v[128:129] op_sel:[0,0,1] op_sel_hi:[1,1,0] neg_lo:[0,0,1]
	v_pk_add_f32 v[128:129], v[148:149], v[138:139] neg_lo:[0,1] neg_hi:[0,1]
	v_pk_add_f32 v[122:123], v[138:139], v[148:149]
	v_pk_mul_f32 v[138:139], v[74:75], v[128:129]
	s_nop 0
	v_pk_fma_f32 v[148:149], v[72:73], v[128:129], v[138:139] op_sel:[0,0,1] op_sel_hi:[1,1,0] neg_hi:[0,0,1]
	v_pk_add_f32 v[138:139], v[144:145], v[140:141] neg_lo:[0,1] neg_hi:[0,1]
	v_pk_add_f32 v[128:129], v[144:145], v[140:141]
	v_pk_mul_f32 v[140:141], v[78:79], v[138:139]
	s_nop 0
	v_pk_fma_f32 v[144:145], v[76:77], v[138:139], v[140:141] op_sel:[0,0,1] op_sel_hi:[1,1,0] neg_lo:[0,0,1]
	v_pk_add_f32 v[138:139], v[120:121], v[132:133]
	v_pk_add_f32 v[120:121], v[132:133], v[120:121] neg_lo:[0,1] neg_hi:[0,1]
	s_nop 0
	v_pk_mul_f32 v[132:133], v[82:83], v[120:121]
	s_nop 0
	v_pk_fma_f32 v[140:141], v[80:81], v[120:121], v[132:133] op_sel:[0,0,1] op_sel_hi:[1,1,0] neg_hi:[0,0,1]
	v_pk_add_f32 v[120:121], v[126:127], v[136:137]
	v_pk_add_f32 v[126:127], v[136:137], v[126:127] neg_lo:[0,1] neg_hi:[0,1]
	s_nop 0
	v_pk_mul_f32 v[132:133], v[82:83], v[126:127]
	s_nop 0
	v_pk_fma_f32 v[136:137], v[80:81], v[126:127], v[132:133] op_sel:[0,0,1] op_sel_hi:[1,1,0] neg_hi:[0,0,1]
	v_pk_add_f32 v[126:127], v[118:119], v[114:115]
	v_pk_add_f32 v[114:115], v[114:115], v[118:119] neg_lo:[0,1] neg_hi:[0,1]
	s_nop 0
	v_pk_mul_f32 v[118:119], v[82:83], v[114:115]
	s_nop 0
	v_pk_fma_f32 v[132:133], v[80:81], v[114:115], v[118:119] op_sel:[0,0,1] op_sel_hi:[1,1,0] neg_hi:[0,0,1]
	v_pk_add_f32 v[118:119], v[146:147], v[142:143] neg_lo:[0,1] neg_hi:[0,1]
	v_pk_add_f32 v[114:115], v[142:143], v[146:147]
	v_pk_mul_f32 v[142:143], v[82:83], v[118:119]
	s_nop 0
	v_pk_fma_f32 v[146:147], v[80:81], v[118:119], v[142:143] op_sel:[0,0,1] op_sel_hi:[1,1,0] neg_hi:[0,0,1]
	v_pk_add_f32 v[118:119], v[116:117], v[124:125]
	v_pk_add_f32 v[116:117], v[124:125], v[116:117] neg_lo:[0,1] neg_hi:[0,1]
	s_nop 0
	v_pk_mul_f32 v[124:125], v[82:83], v[116:117]
	s_nop 0
	v_pk_fma_f32 v[142:143], v[80:81], v[116:117], v[124:125] op_sel:[0,0,1] op_sel_hi:[1,1,0] neg_hi:[0,0,1]
	v_pk_add_f32 v[124:125], v[134:135], v[130:131] neg_lo:[0,1] neg_hi:[0,1]
	v_pk_add_f32 v[116:117], v[130:131], v[134:135]
	v_pk_mul_f32 v[130:131], v[82:83], v[124:125]
	s_nop 0
	v_pk_fma_f32 v[134:135], v[80:81], v[124:125], v[130:131] op_sel:[0,0,1] op_sel_hi:[1,1,0] neg_hi:[0,0,1]
	v_pk_add_f32 v[124:125], v[122:123], v[128:129] neg_lo:[0,1] neg_hi:[0,1]
	v_pk_add_f32 v[122:123], v[128:129], v[122:123]
	v_pk_mul_f32 v[130:131], v[82:83], v[124:125]
	v_pk_add_f32 v[128:129], v[148:149], v[144:145] neg_lo:[0,1] neg_hi:[0,1]
	v_pk_fma_f32 v[150:151], v[80:81], v[124:125], v[130:131] op_sel:[0,0,1] op_sel_hi:[1,1,0] neg_hi:[0,0,1]
	v_pk_mul_f32 v[130:131], v[82:83], v[128:129]
	v_pk_add_f32 v[124:125], v[144:145], v[148:149]
	v_pk_fma_f32 v[144:145], v[80:81], v[128:129], v[130:131] op_sel:[0,0,1] op_sel_hi:[1,1,0] neg_hi:[0,0,1]
	ds_write_b64 v152, v[138:139]
	ds_write_b64 v153, v[140:141] offset:512
	ds_write_b64 v154, v[120:121] offset:1024
	ds_write_b64 v155, v[136:137] offset:1536
	ds_write_b64 v156, v[126:127] offset:2048
	ds_write_b64 v157, v[132:133] offset:2560
	ds_write_b64 v158, v[114:115] offset:3072
	ds_write_b64 v159, v[146:147] offset:3584
	ds_write_b64 v160, v[118:119] offset:4096
	ds_write_b64 v161, v[142:143] offset:4608
	ds_write_b64 v162, v[116:117] offset:5120
	ds_write_b64 v163, v[134:135] offset:5632
	ds_write_b64 v164, v[122:123] offset:6144
	ds_write_b64 v165, v[150:151] offset:6656
	ds_write_b64 v166, v[124:125] offset:7168
	ds_write_b64 v167, v[144:145] offset:7680
	s_andn2_b64 exec, exec, s[12:13]
	s_cbranch_execnz .LBB0_666

.LBB0_669:
	v_and_b32_e32 v130, 0xffffffc0, v111
	v_or_b32_e32 v114, v130, v0
	v_lshl_add_u32 v131, v114, 3, 0
	v_ashrrev_i32_e32 v114, 2, v130
	v_or_b32_e32 v130, 32, v130
	v_ashrrev_i32_e32 v130, 5, v130
	v_add_u32_e32 v152, v131, v114
	v_lshl_add_u32 v153, v130, 3, v131
	ds_read2_b64 v[114:117], v152 offset1:4
	ds_read2_b64 v[118:121], v152 offset0:8 offset1:12
	ds_read2_b64 v[122:125], v152 offset0:16 offset1:20
	ds_read2_b64 v[126:129], v152 offset0:24 offset1:28
	ds_read2_b64 v[130:133], v153 offset0:32 offset1:36
	ds_read2_b64 v[134:137], v153 offset0:40 offset1:44
	ds_read2_b64 v[138:141], v153 offset0:48 offset1:52
	ds_read2_b64 v[142:145], v153 offset0:56 offset1:60
	v_add_u32_e32 v25, 0x200, v25
	s_waitcnt lgkmcnt(3)
	v_pk_add_f32 v[146:147], v[130:131], v[114:115]
	v_pk_add_f32 v[114:115], v[114:115], v[130:131] neg_lo:[0,1] neg_hi:[0,1]
	v_cmp_lt_i32_e32 vcc, s35, v25
	v_pk_mul_f32 v[130:131], v[20:21], v[114:115] op_sel:[0,1] op_sel_hi:[1,0]
	v_add_u32_e32 v111, 0x2000, v111
	v_pk_fma_f32 v[148:149], v[2:3], v[114:115], v[130:131] neg_hi:[0,0,1]
	s_or_b64 s[12:13], vcc, s[12:13]
	v_pk_add_f32 v[114:115], v[116:117], v[132:133]
	v_pk_add_f32 v[116:117], v[116:117], v[132:133] neg_lo:[0,1] neg_hi:[0,1]
	s_nop 0
	v_pk_mul_f32 v[130:131], v[40:41], v[116:117] op_sel:[0,1] op_sel_hi:[1,0]
	s_nop 0
	v_pk_fma_f32 v[132:133], v[38:39], v[116:117], v[130:131] neg_lo:[0,0,1]
	s_waitcnt lgkmcnt(2)
	v_pk_add_f32 v[116:117], v[118:119], v[134:135]
	v_pk_add_f32 v[118:119], v[118:119], v[134:135] neg_lo:[0,1] neg_hi:[0,1]
	s_nop 0
	v_pk_mul_f32 v[130:131], v[44:45], v[118:119] op_sel:[0,1] op_sel_hi:[1,0]
	s_nop 0
	v_pk_fma_f32 v[134:135], v[42:43], v[118:119], v[130:131] neg_lo:[0,0,1]
	v_pk_add_f32 v[118:119], v[120:121], v[136:137]
	v_pk_add_f32 v[120:121], v[120:121], v[136:137] neg_lo:[0,1] neg_hi:[0,1]
	s_nop 0
	v_pk_mul_f32 v[130:131], v[48:49], v[120:121] op_sel:[0,1] op_sel_hi:[1,0]
	s_nop 0
	v_pk_fma_f32 v[136:137], v[32:33], v[120:121], v[130:131] neg_lo:[0,0,1]
	s_waitcnt lgkmcnt(1)
	v_pk_add_f32 v[120:121], v[122:123], v[138:139]
	v_pk_add_f32 v[122:123], v[122:123], v[138:139] neg_lo:[0,1] neg_hi:[0,1]
	s_nop 0
	v_pk_mul_f32 v[130:131], v[52:53], v[122:123] op_sel:[0,1] op_sel_hi:[1,0]
	s_nop 0
	v_pk_fma_f32 v[138:139], v[50:51], v[122:123], v[130:131] neg_lo:[0,0,1]
	v_pk_add_f32 v[122:123], v[124:125], v[140:141]
	v_pk_add_f32 v[124:125], v[124:125], v[140:141] neg_lo:[0,1] neg_hi:[0,1]
	s_nop 0
	v_pk_mul_f32 v[130:131], v[22:23], v[124:125] op_sel:[0,1] op_sel_hi:[1,0]
	s_nop 0
	v_pk_fma_f32 v[140:141], v[46:47], v[124:125], v[130:131] neg_lo:[0,0,1]
	s_waitcnt lgkmcnt(0)
	v_pk_add_f32 v[124:125], v[126:127], v[142:143]
	v_pk_add_f32 v[126:127], v[126:127], v[142:143] neg_lo:[0,1] neg_hi:[0,1]
	s_nop 0
	v_pk_mul_f32 v[130:131], v[34:35], v[126:127] op_sel:[0,1] op_sel_hi:[1,0]
	s_nop 0
	v_pk_fma_f32 v[142:143], v[36:37], v[126:127], v[130:131] neg_lo:[0,0,1]
	v_pk_add_f32 v[126:127], v[128:129], v[144:145]
	v_pk_add_f32 v[128:129], v[128:129], v[144:145] neg_lo:[0,1] neg_hi:[0,1]
	s_nop 0
	v_pk_mul_f32 v[130:131], v[58:59], v[128:129] op_sel:[0,1] op_sel_hi:[1,0]
	s_nop 0
	v_pk_fma_f32 v[144:145], v[30:31], v[128:129], v[130:131] neg_lo:[0,0,1]
	v_pk_add_f32 v[128:129], v[120:121], v[146:147]
	v_pk_add_f32 v[120:121], v[146:147], v[120:121] neg_lo:[0,1] neg_hi:[0,1]
	s_nop 0
	v_pk_mul_f32 v[130:131], v[56:57], v[120:121]
	s_nop 0
	v_pk_fma_f32 v[146:147], v[54:55], v[120:121], v[130:131] op_sel:[0,0,1] op_sel_hi:[1,1,0] neg_hi:[0,0,1]
	v_pk_add_f32 v[120:121], v[114:115], v[122:123]
	v_pk_add_f32 v[114:115], v[114:115], v[122:123] neg_lo:[0,1] neg_hi:[0,1]
	s_nop 0
	v_pk_mul_f32 v[122:123], v[66:67], v[114:115]
	s_nop 0
	v_pk_fma_f32 v[130:131], v[64:65], v[114:115], v[122:123] op_sel:[0,0,1] op_sel_hi:[1,1,0] neg_lo:[0,0,1]
	v_pk_add_f32 v[114:115], v[116:117], v[124:125]
	v_pk_add_f32 v[116:117], v[116:117], v[124:125] neg_lo:[0,1] neg_hi:[0,1]
	s_nop 0
	v_pk_mul_f32 v[122:123], v[70:71], v[116:117]
	s_nop 0
	v_pk_fma_f32 v[124:125], v[68:69], v[116:117], v[122:123] op_sel:[0,0,1] op_sel_hi:[1,1,0] neg_lo:[0,0,1]
	v_pk_add_f32 v[116:117], v[118:119], v[126:127]
	v_pk_add_f32 v[118:119], v[118:119], v[126:127] neg_lo:[0,1] neg_hi:[0,1]
	s_nop 0
	v_pk_mul_f32 v[122:123], v[60:61], v[118:119]
	s_nop 0
	v_pk_fma_f32 v[126:127], v[62:63], v[118:119], v[122:123] op_sel:[0,0,1] op_sel_hi:[1,1,0] neg_lo:[0,0,1]
	v_pk_add_f32 v[122:123], v[148:149], v[138:139] neg_lo:[0,1] neg_hi:[0,1]
	v_pk_add_f32 v[118:119], v[138:139], v[148:149]
	v_pk_mul_f32 v[138:139], v[56:57], v[122:123]
	s_nop 0
	v_pk_fma_f32 v[148:149], v[54:55], v[122:123], v[138:139] op_sel:[0,0,1] op_sel_hi:[1,1,0] neg_hi:[0,0,1]
	v_pk_add_f32 v[122:123], v[132:133], v[140:141]
	v_pk_add_f32 v[132:133], v[132:133], v[140:141] neg_lo:[0,1] neg_hi:[0,1]
	s_nop 0
	v_pk_mul_f32 v[138:139], v[66:67], v[132:133]
	s_nop 0
	v_pk_fma_f32 v[140:141], v[64:65], v[132:133], v[138:139] op_sel:[0,0,1] op_sel_hi:[1,1,0] neg_lo:[0,0,1]
	v_pk_add_f32 v[132:133], v[134:135], v[142:143]
	v_pk_add_f32 v[134:135], v[134:135], v[142:143] neg_lo:[0,1] neg_hi:[0,1]
	s_nop 0
	v_pk_mul_f32 v[138:139], v[70:71], v[134:135]
	s_nop 0
	v_pk_fma_f32 v[142:143], v[68:69], v[134:135], v[138:139] op_sel:[0,0,1] op_sel_hi:[1,1,0] neg_lo:[0,0,1]
	v_pk_add_f32 v[134:135], v[136:137], v[144:145]
	v_pk_add_f32 v[136:137], v[136:137], v[144:145] neg_lo:[0,1] neg_hi:[0,1]
	s_nop 0
	v_pk_mul_f32 v[138:139], v[60:61], v[136:137]
	s_nop 0
	v_pk_fma_f32 v[144:145], v[62:63], v[136:137], v[138:139] op_sel:[0,0,1] op_sel_hi:[1,1,0] neg_lo:[0,0,1]
	v_pk_add_f32 v[136:137], v[114:115], v[128:129]
	v_pk_add_f32 v[114:115], v[128:129], v[114:115] neg_lo:[0,1] neg_hi:[0,1]
	s_nop 0
	v_pk_mul_f32 v[128:129], v[74:75], v[114:115]
	s_nop 0
	v_pk_fma_f32 v[138:139], v[72:73], v[114:115], v[128:129] op_sel:[0,0,1] op_sel_hi:[1,1,0] neg_hi:[0,0,1]
	v_pk_add_f32 v[114:115], v[120:121], v[116:117]
	v_pk_add_f32 v[116:117], v[120:121], v[116:117] neg_lo:[0,1] neg_hi:[0,1]
	s_nop 0
	v_pk_mul_f32 v[120:121], v[78:79], v[116:117]
	s_nop 0
	v_pk_fma_f32 v[128:129], v[76:77], v[116:117], v[120:121] op_sel:[0,0,1] op_sel_hi:[1,1,0] neg_lo:[0,0,1]
	v_pk_add_f32 v[120:121], v[146:147], v[124:125] neg_lo:[0,1] neg_hi:[0,1]
	v_pk_add_f32 v[116:117], v[124:125], v[146:147]
	v_pk_mul_f32 v[124:125], v[74:75], v[120:121]
	s_nop 0
	v_pk_fma_f32 v[146:147], v[72:73], v[120:121], v[124:125] op_sel:[0,0,1] op_sel_hi:[1,1,0] neg_hi:[0,0,1]
	v_pk_add_f32 v[124:125], v[130:131], v[126:127] neg_lo:[0,1] neg_hi:[0,1]
	v_pk_add_f32 v[120:121], v[130:131], v[126:127]
	v_pk_mul_f32 v[126:127], v[78:79], v[124:125]
	s_nop 0
	v_pk_fma_f32 v[130:131], v[76:77], v[124:125], v[126:127] op_sel:[0,0,1] op_sel_hi:[1,1,0] neg_lo:[0,0,1]
	v_pk_add_f32 v[124:125], v[132:133], v[118:119]
	v_pk_add_f32 v[118:119], v[118:119], v[132:133] neg_lo:[0,1] neg_hi:[0,1]
	s_nop 0
	v_pk_mul_f32 v[126:127], v[74:75], v[118:119]
	s_nop 0
	v_pk_fma_f32 v[132:133], v[72:73], v[118:119], v[126:127] op_sel:[0,0,1] op_sel_hi:[1,1,0] neg_hi:[0,0,1]
	v_pk_add_f32 v[118:119], v[122:123], v[134:135]
	v_pk_add_f32 v[122:123], v[122:123], v[134:135] neg_lo:[0,1] neg_hi:[0,1]
	s_nop 0
	v_pk_mul_f32 v[126:127], v[78:79], v[122:123]
	s_nop 0
	v_pk_fma_f32 v[134:135], v[76:77], v[122:123], v[126:127] op_sel:[0,0,1] op_sel_hi:[1,1,0] neg_lo:[0,0,1]
	v_pk_add_f32 v[126:127], v[148:149], v[142:143] neg_lo:[0,1] neg_hi:[0,1]
	v_pk_add_f32 v[122:123], v[142:143], v[148:149]
	v_pk_mul_f32 v[142:143], v[74:75], v[126:127]
	s_nop 0
	v_pk_fma_f32 v[148:149], v[72:73], v[126:127], v[142:143] op_sel:[0,0,1] op_sel_hi:[1,1,0] neg_hi:[0,0,1]
	v_pk_add_f32 v[126:127], v[140:141], v[144:145]
	v_pk_add_f32 v[140:141], v[140:141], v[144:145] neg_lo:[0,1] neg_hi:[0,1]
	s_nop 0
	v_pk_mul_f32 v[142:143], v[78:79], v[140:141]
	s_nop 0
	v_pk_fma_f32 v[144:145], v[76:77], v[140:141], v[142:143] op_sel:[0,0,1] op_sel_hi:[1,1,0] neg_lo:[0,0,1]
	v_pk_add_f32 v[140:141], v[114:115], v[136:137]
	v_pk_add_f32 v[114:115], v[136:137], v[114:115] neg_lo:[0,1] neg_hi:[0,1]
	s_nop 0
	v_pk_mul_f32 v[136:137], v[82:83], v[114:115]
	s_nop 0
	v_pk_fma_f32 v[142:143], v[80:81], v[114:115], v[136:137] op_sel:[0,0,1] op_sel_hi:[1,1,0] neg_hi:[0,0,1]
	v_pk_add_f32 v[114:115], v[128:129], v[138:139]
	v_pk_add_f32 v[128:129], v[138:139], v[128:129] neg_lo:[0,1] neg_hi:[0,1]
	s_nop 0
	v_pk_mul_f32 v[136:137], v[82:83], v[128:129]
	s_nop 0
	v_pk_fma_f32 v[138:139], v[80:81], v[128:129], v[136:137] op_sel:[0,0,1] op_sel_hi:[1,1,0] neg_hi:[0,0,1]
	v_pk_add_f32 v[128:129], v[120:121], v[116:117]
	v_pk_add_f32 v[116:117], v[116:117], v[120:121] neg_lo:[0,1] neg_hi:[0,1]
	s_nop 0
	v_pk_mul_f32 v[120:121], v[82:83], v[116:117]
	s_nop 0
	v_pk_fma_f32 v[136:137], v[80:81], v[116:117], v[120:121] op_sel:[0,0,1] op_sel_hi:[1,1,0] neg_hi:[0,0,1]
	v_pk_add_f32 v[120:121], v[146:147], v[130:131] neg_lo:[0,1] neg_hi:[0,1]
	v_pk_add_f32 v[116:117], v[130:131], v[146:147]
	v_pk_mul_f32 v[130:131], v[82:83], v[120:121]
	s_nop 0
	v_pk_fma_f32 v[146:147], v[80:81], v[120:121], v[130:131] op_sel:[0,0,1] op_sel_hi:[1,1,0] neg_hi:[0,0,1]
	v_pk_add_f32 v[120:121], v[118:119], v[124:125]
	v_pk_add_f32 v[118:119], v[124:125], v[118:119] neg_lo:[0,1] neg_hi:[0,1]
	s_nop 0
	v_pk_mul_f32 v[124:125], v[82:83], v[118:119]
	s_nop 0
	v_pk_fma_f32 v[130:131], v[80:81], v[118:119], v[124:125] op_sel:[0,0,1] op_sel_hi:[1,1,0] neg_hi:[0,0,1]
	v_pk_add_f32 v[124:125], v[132:133], v[134:135] neg_lo:[0,1] neg_hi:[0,1]
	v_pk_add_f32 v[118:119], v[134:135], v[132:133]
	v_pk_mul_f32 v[132:133], v[82:83], v[124:125]
	s_nop 0
	v_pk_fma_f32 v[134:135], v[80:81], v[124:125], v[132:133] op_sel:[0,0,1] op_sel_hi:[1,1,0] neg_hi:[0,0,1]
	v_pk_add_f32 v[124:125], v[122:123], v[126:127] neg_lo:[0,1] neg_hi:[0,1]
	v_pk_add_f32 v[122:123], v[126:127], v[122:123]
	v_pk_mul_f32 v[132:133], v[82:83], v[124:125]
	v_pk_add_f32 v[126:127], v[148:149], v[144:145] neg_lo:[0,1] neg_hi:[0,1]
	v_pk_fma_f32 v[150:151], v[80:81], v[124:125], v[132:133] op_sel:[0,0,1] op_sel_hi:[1,1,0] neg_hi:[0,0,1]
	v_pk_mul_f32 v[132:133], v[82:83], v[126:127]
	v_pk_add_f32 v[124:125], v[144:145], v[148:149]
	v_pk_fma_f32 v[144:145], v[80:81], v[126:127], v[132:133] op_sel:[0,0,1] op_sel_hi:[1,1,0] neg_hi:[0,0,1]
	ds_write2_b64 v152, v[140:141], v[142:143] offset1:4
	ds_write2_b64 v152, v[114:115], v[138:139] offset0:8 offset1:12
	ds_write2_b64 v152, v[128:129], v[136:137] offset0:16 offset1:20
	ds_write2_b64 v152, v[116:117], v[146:147] offset0:24 offset1:28
	ds_write2_b64 v153, v[120:121], v[130:131] offset0:32 offset1:36
	ds_write2_b64 v153, v[118:119], v[134:135] offset0:40 offset1:44
	ds_write2_b64 v153, v[122:123], v[150:151] offset0:48 offset1:52
	ds_write2_b64 v153, v[124:125], v[144:145] offset0:56 offset1:60
	s_andn2_b64 exec, exec, s[12:13]
	s_cbranch_execnz .LBB0_669

.LBB0_672:
	v_ashrrev_i32_e32 v20, 5, v3
	v_lshl_add_u32 v25, v20, 3, v2
	ds_read2_b64 v[20:23], v25 offset1:1
	ds_read2_b64 v[30:33], v25 offset0:2 offset1:3
	v_add_u32_e32 v0, 0x200, v0
	v_cmp_lt_i32_e32 vcc, s43, v0
	v_add_u32_e32 v3, 0x800, v3
	v_add_u32_e32 v2, 0x4000, v2
	s_waitcnt lgkmcnt(0)
	v_pk_add_f32 v[34:35], v[30:31], v[20:21]
	v_pk_add_f32 v[20:21], v[20:21], v[30:31] neg_lo:[0,1] neg_hi:[0,1]
	v_pk_add_f32 v[30:31], v[22:23], v[32:33] neg_lo:[0,1] neg_hi:[0,1]
	v_pk_add_f32 v[22:23], v[22:23], v[32:33]
	v_pk_mul_f32 v[32:33], v[20:21], 0 op_sel_hi:[1,0]
	v_pk_fma_f32 v[36:37], v[30:31], 0, v[30:31] op_sel:[0,0,1] op_sel_hi:[1,0,0] neg_hi:[0,0,1]
	v_pk_add_f32 v[38:39], v[34:35], v[22:23] neg_lo:[0,1] neg_hi:[0,1]
	v_pk_add_f32 v[22:23], v[22:23], v[34:35]
	v_pk_add_f32 v[34:35], v[20:21], v[32:33] op_sel:[0,1] op_sel_hi:[1,0]
	v_pk_add_f32 v[20:21], v[20:21], v[32:33] op_sel:[0,1] op_sel_hi:[1,0] neg_lo:[0,1] neg_hi:[0,1]
	v_pk_mul_f32 v[30:31], v[38:39], 0 op_sel_hi:[1,0]
	v_mov_b32_e32 v35, v21
	v_pk_add_f32 v[20:21], v[38:39], v[30:31] op_sel:[0,1] op_sel_hi:[1,0]
	v_pk_add_f32 v[30:31], v[38:39], v[30:31] op_sel:[0,1] op_sel_hi:[1,0] neg_lo:[0,1] neg_hi:[0,1]
	v_pk_add_f32 v[32:33], v[36:37], v[34:35]
	v_pk_add_f32 v[34:35], v[34:35], v[36:37] neg_lo:[0,1] neg_hi:[0,1]
	v_mov_b32_e32 v21, v31
	v_pk_mul_f32 v[30:31], v[34:35], 0 op_sel_hi:[1,0]
	ds_write2_b64 v25, v[22:23], v[20:21] offset1:1
	v_pk_add_f32 v[20:21], v[34:35], v[30:31] op_sel:[0,1] op_sel_hi:[1,0]
	v_pk_add_f32 v[22:23], v[34:35], v[30:31] op_sel:[0,1] op_sel_hi:[1,0] neg_lo:[0,1] neg_hi:[0,1]
	s_or_b64 s[12:13], vcc, s[12:13]
	v_mov_b32_e32 v21, v23
	ds_write2_b64 v25, v[32:33], v[20:21] offset0:2 offset1:3
	s_andn2_b64 exec, exec, s[12:13]
	s_cbranch_execnz .LBB0_672

.LBB0_693:
	s_waitcnt vmcnt(0)
	v_ashrrev_i32_e32 v20, 5, v3
	v_lshl_add_u32 v25, v20, 3, v2
	ds_read2_b64 v[20:23], v25 offset0:2 offset1:3
	ds_read2_b64 v[30:33], v25 offset1:1
	v_add_u32_e32 v0, 0x200, v0
	v_cmp_lt_i32_e32 vcc, s43, v0
	v_add_u32_e32 v2, 0x4000, v2
	v_add_u32_e32 v3, 0x800, v3
	s_waitcnt lgkmcnt(0)
	v_pk_mul_f32 v[34:35], v[32:33], 0 op_sel_hi:[1,0]
	s_or_b64 s[12:13], vcc, s[12:13]
	v_pk_add_f32 v[36:37], v[32:33], v[34:35] op_sel:[0,1] op_sel_hi:[1,0] neg_lo:[0,1] neg_hi:[0,1]
	v_pk_add_f32 v[32:33], v[32:33], v[34:35] op_sel:[0,1] op_sel_hi:[1,0]
	v_pk_mul_f32 v[34:35], v[22:23], 0 op_sel_hi:[1,0]
	v_mov_b32_e32 v37, v33
	v_pk_add_f32 v[32:33], v[30:31], v[36:37]
	v_pk_add_f32 v[30:31], v[30:31], v[36:37] neg_lo:[0,1] neg_hi:[0,1]
	v_pk_add_f32 v[36:37], v[22:23], v[34:35] op_sel:[0,1] op_sel_hi:[1,0] neg_lo:[0,1] neg_hi:[0,1]
	v_pk_add_f32 v[22:23], v[22:23], v[34:35] op_sel:[0,1] op_sel_hi:[1,0]
	s_nop 0
	v_mov_b32_e32 v37, v23
	v_pk_add_f32 v[22:23], v[20:21], v[36:37] neg_lo:[0,1] neg_hi:[0,1]
	v_pk_add_f32 v[20:21], v[20:21], v[36:37]
	s_nop 0
	v_pk_mul_f32 v[34:35], v[20:21], 0 op_sel_hi:[1,0]
	s_nop 0
	v_pk_add_f32 v[36:37], v[20:21], v[34:35] op_sel:[0,1] op_sel_hi:[1,0] neg_lo:[0,1] neg_hi:[0,1]
	v_pk_add_f32 v[20:21], v[20:21], v[34:35] op_sel:[0,1] op_sel_hi:[1,0]
	v_pk_fma_f32 v[34:35], v[22:23], 0, v[22:23] op_sel:[0,0,1] op_sel_hi:[1,0,0] neg_lo:[0,0,1]
	v_mov_b32_e32 v37, v21
	v_pk_add_f32 v[20:21], v[32:33], v[36:37]
	v_pk_add_f32 v[22:23], v[30:31], v[34:35]
	v_pk_add_f32 v[32:33], v[32:33], v[36:37] neg_lo:[0,1] neg_hi:[0,1]
	v_pk_add_f32 v[30:31], v[30:31], v[34:35] neg_lo:[0,1] neg_hi:[0,1]
	ds_write2_b64 v25, v[20:21], v[22:23] offset1:1
	ds_write2_b64 v25, v[32:33], v[30:31] offset0:2 offset1:3
	s_andn2_b64 exec, exec, s[12:13]
	s_cbranch_execnz .LBB0_693

.LBB0_696:
	v_and_b32_e32 v126, 0xffffffc0, v111
	v_or_b32_e32 v114, v126, v0
	v_lshl_add_u32 v127, v114, 3, 0
	v_ashrrev_i32_e32 v114, 2, v126
	v_or_b32_e32 v126, 32, v126
	v_ashrrev_i32_e32 v126, 5, v126
	v_add_u32_e32 v150, v127, v114
	v_lshl_add_u32 v151, v126, 3, v127
	ds_read2_b64 v[114:117], v150 offset0:8 offset1:12
	ds_read2_b64 v[118:121], v150 offset0:16 offset1:20
	ds_read2_b64 v[122:125], v150 offset0:24 offset1:28
	ds_read2_b64 v[126:129], v151 offset0:32 offset1:36
	ds_read2_b64 v[130:133], v151 offset0:40 offset1:44
	ds_read2_b64 v[134:137], v151 offset0:48 offset1:52
	ds_read2_b64 v[138:141], v151 offset0:56 offset1:60
	ds_read2_b64 v[142:145], v150 offset1:4
	v_add_u32_e32 v25, 0x200, v25
	v_cmp_lt_i32_e32 vcc, s35, v25
	v_add_u32_e32 v111, 0x2000, v111
	s_or_b64 s[12:13], vcc, s[12:13]
	s_waitcnt lgkmcnt(0)
	v_pk_mul_f32 v[146:147], v[20:21], v[144:145]
	s_nop 0
	v_pk_fma_f32 v[148:149], v[2:3], v[144:145], v[146:147] op_sel:[0,0,1] op_sel_hi:[1,1,0] neg_lo:[0,0,1]
	v_pk_mul_f32 v[146:147], v[20:21], v[116:117]
	v_pk_add_f32 v[144:145], v[142:143], v[148:149]
	v_pk_add_f32 v[142:143], v[142:143], v[148:149] neg_lo:[0,1] neg_hi:[0,1]
	v_pk_fma_f32 v[148:149], v[2:3], v[116:117], v[146:147] op_sel:[0,0,1] op_sel_hi:[1,1,0] neg_lo:[0,0,1]
	v_pk_mul_f32 v[146:147], v[20:21], v[120:121]
	v_pk_add_f32 v[116:117], v[114:115], v[148:149]
	v_pk_add_f32 v[114:115], v[114:115], v[148:149] neg_lo:[0,1] neg_hi:[0,1]
	v_pk_fma_f32 v[148:149], v[2:3], v[120:121], v[146:147] op_sel:[0,0,1] op_sel_hi:[1,1,0] neg_lo:[0,0,1]
	v_pk_mul_f32 v[146:147], v[20:21], v[124:125]
	v_pk_add_f32 v[120:121], v[118:119], v[148:149]
	v_pk_add_f32 v[118:119], v[118:119], v[148:149] neg_lo:[0,1] neg_hi:[0,1]
	v_pk_fma_f32 v[148:149], v[2:3], v[124:125], v[146:147] op_sel:[0,0,1] op_sel_hi:[1,1,0] neg_lo:[0,0,1]
	v_pk_mul_f32 v[146:147], v[20:21], v[128:129]
	v_pk_add_f32 v[124:125], v[122:123], v[148:149]
	v_pk_add_f32 v[122:123], v[122:123], v[148:149] neg_lo:[0,1] neg_hi:[0,1]
	v_pk_fma_f32 v[148:149], v[2:3], v[128:129], v[146:147] op_sel:[0,0,1] op_sel_hi:[1,1,0] neg_lo:[0,0,1]
	v_pk_mul_f32 v[146:147], v[20:21], v[132:133]
	v_pk_add_f32 v[128:129], v[126:127], v[148:149]
	v_pk_add_f32 v[126:127], v[126:127], v[148:149] neg_lo:[0,1] neg_hi:[0,1]
	v_pk_fma_f32 v[148:149], v[2:3], v[132:133], v[146:147] op_sel:[0,0,1] op_sel_hi:[1,1,0] neg_lo:[0,0,1]
	v_pk_mul_f32 v[146:147], v[20:21], v[136:137]
	v_pk_add_f32 v[132:133], v[130:131], v[148:149]
	v_pk_add_f32 v[130:131], v[130:131], v[148:149] neg_lo:[0,1] neg_hi:[0,1]
	v_pk_fma_f32 v[148:149], v[2:3], v[136:137], v[146:147] op_sel:[0,0,1] op_sel_hi:[1,1,0] neg_lo:[0,0,1]
	v_pk_mul_f32 v[146:147], v[20:21], v[140:141]
	v_pk_add_f32 v[136:137], v[134:135], v[148:149]
	v_pk_add_f32 v[134:135], v[134:135], v[148:149] neg_lo:[0,1] neg_hi:[0,1]
	v_pk_fma_f32 v[148:149], v[2:3], v[140:141], v[146:147] op_sel:[0,0,1] op_sel_hi:[1,1,0] neg_lo:[0,0,1]
	v_pk_mul_f32 v[146:147], v[30:31], v[116:117]
	v_pk_add_f32 v[140:141], v[138:139], v[148:149]
	v_pk_add_f32 v[138:139], v[138:139], v[148:149] neg_lo:[0,1] neg_hi:[0,1]
	v_pk_fma_f32 v[148:149], v[22:23], v[116:117], v[146:147] op_sel:[0,0,1] op_sel_hi:[1,1,0] neg_lo:[0,0,1]
	v_pk_mul_f32 v[146:147], v[38:39], v[114:115]
	v_pk_add_f32 v[116:117], v[148:149], v[144:145]
	v_pk_add_f32 v[144:145], v[144:145], v[148:149] neg_lo:[0,1] neg_hi:[0,1]
	v_pk_fma_f32 v[148:149], v[36:37], v[114:115], v[146:147] op_sel:[0,0,1] op_sel_hi:[1,1,0] neg_hi:[0,0,1]
	v_pk_mul_f32 v[146:147], v[30:31], v[124:125]
	v_pk_add_f32 v[114:115], v[148:149], v[142:143]
	v_pk_add_f32 v[142:143], v[142:143], v[148:149] neg_lo:[0,1] neg_hi:[0,1]
	v_pk_fma_f32 v[148:149], v[22:23], v[124:125], v[146:147] op_sel:[0,0,1] op_sel_hi:[1,1,0] neg_lo:[0,0,1]
	v_pk_mul_f32 v[146:147], v[38:39], v[122:123]
	v_pk_add_f32 v[124:125], v[120:121], v[148:149]
	v_pk_add_f32 v[120:121], v[120:121], v[148:149] neg_lo:[0,1] neg_hi:[0,1]
	v_pk_fma_f32 v[148:149], v[36:37], v[122:123], v[146:147] op_sel:[0,0,1] op_sel_hi:[1,1,0] neg_hi:[0,0,1]
	v_pk_mul_f32 v[146:147], v[30:31], v[132:133]
	v_pk_add_f32 v[122:123], v[118:119], v[148:149]
	v_pk_add_f32 v[118:119], v[118:119], v[148:149] neg_lo:[0,1] neg_hi:[0,1]
	v_pk_fma_f32 v[148:149], v[22:23], v[132:133], v[146:147] op_sel:[0,0,1] op_sel_hi:[1,1,0] neg_lo:[0,0,1]
	v_pk_mul_f32 v[146:147], v[38:39], v[130:131]
	v_pk_add_f32 v[132:133], v[128:129], v[148:149]
	v_pk_add_f32 v[128:129], v[128:129], v[148:149] neg_lo:[0,1] neg_hi:[0,1]
	v_pk_fma_f32 v[148:149], v[36:37], v[130:131], v[146:147] op_sel:[0,0,1] op_sel_hi:[1,1,0] neg_hi:[0,0,1]
	v_pk_mul_f32 v[146:147], v[30:31], v[140:141]
	v_pk_add_f32 v[130:131], v[126:127], v[148:149]
	v_pk_add_f32 v[126:127], v[126:127], v[148:149] neg_lo:[0,1] neg_hi:[0,1]
	v_pk_fma_f32 v[148:149], v[22:23], v[140:141], v[146:147] op_sel:[0,0,1] op_sel_hi:[1,1,0] neg_lo:[0,0,1]
	v_pk_mul_f32 v[146:147], v[38:39], v[138:139]
	v_pk_add_f32 v[140:141], v[136:137], v[148:149]
	v_pk_add_f32 v[136:137], v[136:137], v[148:149] neg_lo:[0,1] neg_hi:[0,1]
	v_pk_fma_f32 v[148:149], v[36:37], v[138:139], v[146:147] op_sel:[0,0,1] op_sel_hi:[1,1,0] neg_hi:[0,0,1]
	v_pk_mul_f32 v[146:147], v[34:35], v[124:125]
	v_pk_add_f32 v[138:139], v[134:135], v[148:149]
	v_pk_add_f32 v[134:135], v[134:135], v[148:149] neg_lo:[0,1] neg_hi:[0,1]
	v_pk_fma_f32 v[148:149], v[32:33], v[124:125], v[146:147] op_sel:[0,0,1] op_sel_hi:[1,1,0] neg_lo:[0,0,1]
	v_pk_mul_f32 v[146:147], v[46:47], v[122:123]
	v_pk_add_f32 v[124:125], v[116:117], v[148:149]
	v_pk_add_f32 v[116:117], v[116:117], v[148:149] neg_lo:[0,1] neg_hi:[0,1]
	v_pk_fma_f32 v[148:149], v[44:45], v[122:123], v[146:147] op_sel:[0,0,1] op_sel_hi:[1,1,0] neg_hi:[0,0,1]
	v_pk_mul_f32 v[146:147], v[50:51], v[120:121]
	v_pk_add_f32 v[122:123], v[114:115], v[148:149]
	v_pk_add_f32 v[114:115], v[114:115], v[148:149] neg_lo:[0,1] neg_hi:[0,1]
	v_pk_fma_f32 v[148:149], v[48:49], v[120:121], v[146:147] op_sel:[0,0,1] op_sel_hi:[1,1,0] neg_hi:[0,0,1]
	v_pk_mul_f32 v[146:147], v[40:41], v[118:119]
	v_pk_add_f32 v[120:121], v[144:145], v[148:149]
	v_pk_add_f32 v[144:145], v[144:145], v[148:149] neg_lo:[0,1] neg_hi:[0,1]
	v_pk_fma_f32 v[148:149], v[42:43], v[118:119], v[146:147] op_sel:[0,0,1] op_sel_hi:[1,1,0] neg_hi:[0,0,1]
	v_pk_mul_f32 v[146:147], v[34:35], v[140:141]
	v_pk_add_f32 v[118:119], v[142:143], v[148:149]
	v_pk_add_f32 v[142:143], v[142:143], v[148:149] neg_lo:[0,1] neg_hi:[0,1]
	v_pk_fma_f32 v[148:149], v[32:33], v[140:141], v[146:147] op_sel:[0,0,1] op_sel_hi:[1,1,0] neg_lo:[0,0,1]
	v_pk_mul_f32 v[146:147], v[46:47], v[138:139]
	v_pk_add_f32 v[140:141], v[132:133], v[148:149]
	v_pk_add_f32 v[132:133], v[132:133], v[148:149] neg_lo:[0,1] neg_hi:[0,1]
	v_pk_fma_f32 v[148:149], v[44:45], v[138:139], v[146:147] op_sel:[0,0,1] op_sel_hi:[1,1,0] neg_hi:[0,0,1]
	v_pk_mul_f32 v[146:147], v[50:51], v[136:137]
	v_pk_add_f32 v[138:139], v[130:131], v[148:149]
	v_pk_add_f32 v[130:131], v[130:131], v[148:149] neg_lo:[0,1] neg_hi:[0,1]
	v_pk_fma_f32 v[148:149], v[48:49], v[136:137], v[146:147] op_sel:[0,0,1] op_sel_hi:[1,1,0] neg_hi:[0,0,1]
	v_pk_mul_f32 v[146:147], v[40:41], v[134:135]
	v_pk_add_f32 v[136:137], v[128:129], v[148:149]
	v_pk_add_f32 v[128:129], v[128:129], v[148:149] neg_lo:[0,1] neg_hi:[0,1]
	v_pk_fma_f32 v[148:149], v[42:43], v[134:135], v[146:147] op_sel:[0,0,1] op_sel_hi:[1,1,0] neg_hi:[0,0,1]
	v_pk_mul_f32 v[146:147], v[54:55], v[140:141] op_sel:[0,1] op_sel_hi:[1,0]
	v_pk_add_f32 v[134:135], v[126:127], v[148:149]
	v_pk_add_f32 v[126:127], v[126:127], v[148:149] neg_lo:[0,1] neg_hi:[0,1]
	v_pk_fma_f32 v[148:149], v[52:53], v[140:141], v[146:147] neg_lo:[0,0,1]
	v_pk_mul_f32 v[146:147], v[64:65], v[138:139] op_sel:[0,1] op_sel_hi:[1,0]
	v_pk_add_f32 v[140:141], v[124:125], v[148:149]
	v_pk_add_f32 v[124:125], v[124:125], v[148:149] neg_lo:[0,1] neg_hi:[0,1]
	v_pk_fma_f32 v[148:149], v[60:61], v[138:139], v[146:147] neg_hi:[0,0,1]
	v_pk_mul_f32 v[146:147], v[72:73], v[136:137] op_sel:[0,1] op_sel_hi:[1,0]
	v_pk_add_f32 v[138:139], v[122:123], v[148:149]
	v_pk_add_f32 v[122:123], v[122:123], v[148:149] neg_lo:[0,1] neg_hi:[0,1]
	v_pk_fma_f32 v[148:149], v[70:71], v[136:137], v[146:147] neg_hi:[0,0,1]
	v_pk_mul_f32 v[146:147], v[76:77], v[134:135] op_sel:[0,1] op_sel_hi:[1,0]
	v_pk_add_f32 v[136:137], v[120:121], v[148:149]
	v_pk_add_f32 v[120:121], v[120:121], v[148:149] neg_lo:[0,1] neg_hi:[0,1]
	v_pk_fma_f32 v[148:149], v[62:63], v[134:135], v[146:147] neg_hi:[0,0,1]
	v_pk_mul_f32 v[146:147], v[80:81], v[132:133] op_sel:[0,1] op_sel_hi:[1,0]
	v_pk_add_f32 v[134:135], v[118:119], v[148:149]
	v_pk_add_f32 v[118:119], v[118:119], v[148:149] neg_lo:[0,1] neg_hi:[0,1]
	v_pk_fma_f32 v[148:149], v[78:79], v[132:133], v[146:147] neg_hi:[0,0,1]
	v_pk_mul_f32 v[146:147], v[56:57], v[130:131] op_sel:[0,1] op_sel_hi:[1,0]
	v_pk_add_f32 v[132:133], v[116:117], v[148:149]
	v_pk_add_f32 v[116:117], v[116:117], v[148:149] neg_lo:[0,1] neg_hi:[0,1]
	v_pk_fma_f32 v[148:149], v[74:75], v[130:131], v[146:147] neg_hi:[0,0,1]
	v_pk_mul_f32 v[146:147], v[66:67], v[128:129] op_sel:[0,1] op_sel_hi:[1,0]
	v_pk_add_f32 v[130:131], v[114:115], v[148:149]
	v_pk_add_f32 v[114:115], v[114:115], v[148:149] neg_lo:[0,1] neg_hi:[0,1]
	v_pk_fma_f32 v[148:149], v[68:69], v[128:129], v[146:147] neg_hi:[0,0,1]
	v_pk_mul_f32 v[146:147], v[82:83], v[126:127] op_sel:[0,1] op_sel_hi:[1,0]
	v_pk_add_f32 v[128:129], v[144:145], v[148:149]
	v_pk_add_f32 v[144:145], v[144:145], v[148:149] neg_lo:[0,1] neg_hi:[0,1]
	v_pk_fma_f32 v[148:149], v[58:59], v[126:127], v[146:147] neg_hi:[0,0,1]
	s_nop 0
	v_pk_add_f32 v[126:127], v[142:143], v[148:149]
	v_pk_add_f32 v[142:143], v[142:143], v[148:149] neg_lo:[0,1] neg_hi:[0,1]
	ds_write2_b64 v150, v[140:141], v[138:139] offset1:4
	ds_write2_b64 v150, v[136:137], v[134:135] offset0:8 offset1:12
	ds_write2_b64 v150, v[132:133], v[130:131] offset0:16 offset1:20
	ds_write2_b64 v150, v[128:129], v[126:127] offset0:24 offset1:28
	ds_write2_b64 v151, v[124:125], v[122:123] offset0:32 offset1:36
	ds_write2_b64 v151, v[120:121], v[118:119] offset0:40 offset1:44
	ds_write2_b64 v151, v[116:117], v[114:115] offset0:48 offset1:52
	ds_write2_b64 v151, v[144:145], v[142:143] offset0:56 offset1:60
	s_andn2_b64 exec, exec, s[12:13]
	s_cbranch_execnz .LBB0_696

.LBB0_699:
	v_and_or_b32 v140, v111, s42, v0
	v_ashrrev_i32_e32 v114, 5, v140
	v_lshl_add_u32 v141, v140, 3, 0
	v_lshl_add_u32 v150, v114, 3, v141
	v_or_b32_e32 v114, 64, v140
	v_ashrrev_i32_e32 v114, 5, v114
	v_lshl_add_u32 v151, v114, 3, v141
	v_or_b32_e32 v114, 0x80, v140
	v_or_b32_e32 v116, 0xc0, v140
	v_or_b32_e32 v118, 0x100, v140
	v_or_b32_e32 v120, 0x140, v140
	v_or_b32_e32 v122, 0x180, v140
	v_or_b32_e32 v124, 0x1c0, v140
	v_or_b32_e32 v126, 0x200, v140
	v_or_b32_e32 v128, 0x240, v140
	v_or_b32_e32 v130, 0x280, v140
	v_or_b32_e32 v132, 0x2c0, v140
	v_or_b32_e32 v134, 0x300, v140
	v_or_b32_e32 v136, 0x340, v140
	v_or_b32_e32 v138, 0x380, v140
	v_or_b32_e32 v140, 0x3c0, v140
	v_ashrrev_i32_e32 v114, 5, v114
	v_ashrrev_i32_e32 v116, 5, v116
	v_ashrrev_i32_e32 v118, 5, v118
	v_ashrrev_i32_e32 v120, 5, v120
	v_ashrrev_i32_e32 v122, 5, v122
	v_ashrrev_i32_e32 v124, 5, v124
	v_ashrrev_i32_e32 v126, 5, v126
	v_ashrrev_i32_e32 v128, 5, v128
	v_ashrrev_i32_e32 v130, 5, v130
	v_ashrrev_i32_e32 v132, 5, v132
	v_ashrrev_i32_e32 v134, 5, v134
	v_ashrrev_i32_e32 v136, 5, v136
	v_ashrrev_i32_e32 v138, 5, v138
	v_ashrrev_i32_e32 v140, 5, v140
	v_lshl_add_u32 v152, v114, 3, v141
	v_lshl_add_u32 v153, v116, 3, v141
	v_lshl_add_u32 v154, v118, 3, v141
	v_lshl_add_u32 v155, v120, 3, v141
	v_lshl_add_u32 v156, v122, 3, v141
	v_lshl_add_u32 v157, v124, 3, v141
	v_lshl_add_u32 v158, v126, 3, v141
	v_lshl_add_u32 v159, v128, 3, v141
	v_lshl_add_u32 v160, v130, 3, v141
	v_lshl_add_u32 v161, v132, 3, v141
	v_lshl_add_u32 v162, v134, 3, v141
	v_lshl_add_u32 v163, v136, 3, v141
	v_lshl_add_u32 v164, v138, 3, v141
	v_lshl_add_u32 v165, v140, 3, v141
	ds_read_b64 v[114:115], v152 offset:1024
	ds_read_b64 v[116:117], v153 offset:1536
	ds_read_b64 v[118:119], v154 offset:2048
	ds_read_b64 v[120:121], v155 offset:2560
	ds_read_b64 v[122:123], v156 offset:3072
	ds_read_b64 v[124:125], v157 offset:3584
	ds_read_b64 v[126:127], v158 offset:4096
	ds_read_b64 v[128:129], v159 offset:4608
	ds_read_b64 v[130:131], v160 offset:5120
	ds_read_b64 v[132:133], v161 offset:5632
	ds_read_b64 v[134:135], v162 offset:6144
	ds_read_b64 v[136:137], v163 offset:6656
	ds_read_b64 v[138:139], v164 offset:7168
	ds_read_b64 v[140:141], v165 offset:7680
	ds_read_b64 v[142:143], v151 offset:512
	ds_read_b64 v[144:145], v150
	v_add_u32_e32 v25, 0x200, v25
	v_cmp_lt_i32_e32 vcc, s35, v25
	v_add_u32_e32 v111, 0x2000, v111
	s_waitcnt lgkmcnt(1)
	v_pk_mul_f32 v[146:147], v[20:21], v[142:143]
	s_or_b64 s[12:13], vcc, s[12:13]
	v_pk_fma_f32 v[148:149], v[2:3], v[142:143], v[146:147] op_sel:[0,0,1] op_sel_hi:[1,1,0] neg_lo:[0,0,1]
	v_pk_mul_f32 v[146:147], v[20:21], v[116:117]
	s_waitcnt lgkmcnt(0)
	v_pk_add_f32 v[142:143], v[144:145], v[148:149]
	v_pk_add_f32 v[144:145], v[144:145], v[148:149] neg_lo:[0,1] neg_hi:[0,1]
	v_pk_fma_f32 v[148:149], v[2:3], v[116:117], v[146:147] op_sel:[0,0,1] op_sel_hi:[1,1,0] neg_lo:[0,0,1]
	v_pk_mul_f32 v[146:147], v[20:21], v[120:121]
	v_pk_add_f32 v[116:117], v[114:115], v[148:149]
	v_pk_add_f32 v[114:115], v[114:115], v[148:149] neg_lo:[0,1] neg_hi:[0,1]
	v_pk_fma_f32 v[148:149], v[2:3], v[120:121], v[146:147] op_sel:[0,0,1] op_sel_hi:[1,1,0] neg_lo:[0,0,1]
	v_pk_mul_f32 v[146:147], v[20:21], v[124:125]
	v_pk_add_f32 v[120:121], v[118:119], v[148:149]
	v_pk_add_f32 v[118:119], v[118:119], v[148:149] neg_lo:[0,1] neg_hi:[0,1]
	v_pk_fma_f32 v[148:149], v[2:3], v[124:125], v[146:147] op_sel:[0,0,1] op_sel_hi:[1,1,0] neg_lo:[0,0,1]
	v_pk_mul_f32 v[146:147], v[20:21], v[128:129]
	v_pk_add_f32 v[124:125], v[122:123], v[148:149]
	v_pk_add_f32 v[122:123], v[122:123], v[148:149] neg_lo:[0,1] neg_hi:[0,1]
	v_pk_fma_f32 v[148:149], v[2:3], v[128:129], v[146:147] op_sel:[0,0,1] op_sel_hi:[1,1,0] neg_lo:[0,0,1]
	v_pk_mul_f32 v[146:147], v[20:21], v[132:133]
	v_pk_add_f32 v[128:129], v[126:127], v[148:149]
	v_pk_add_f32 v[126:127], v[126:127], v[148:149] neg_lo:[0,1] neg_hi:[0,1]
	v_pk_fma_f32 v[148:149], v[2:3], v[132:133], v[146:147] op_sel:[0,0,1] op_sel_hi:[1,1,0] neg_lo:[0,0,1]
	v_pk_mul_f32 v[146:147], v[20:21], v[136:137]
	v_pk_add_f32 v[132:133], v[130:131], v[148:149]
	v_pk_add_f32 v[130:131], v[130:131], v[148:149] neg_lo:[0,1] neg_hi:[0,1]
	v_pk_fma_f32 v[148:149], v[2:3], v[136:137], v[146:147] op_sel:[0,0,1] op_sel_hi:[1,1,0] neg_lo:[0,0,1]
	v_pk_mul_f32 v[146:147], v[20:21], v[140:141]
	v_pk_add_f32 v[136:137], v[134:135], v[148:149]
	v_pk_add_f32 v[134:135], v[134:135], v[148:149] neg_lo:[0,1] neg_hi:[0,1]
	v_pk_fma_f32 v[148:149], v[2:3], v[140:141], v[146:147] op_sel:[0,0,1] op_sel_hi:[1,1,0] neg_lo:[0,0,1]
	v_pk_mul_f32 v[146:147], v[30:31], v[116:117]
	v_pk_add_f32 v[140:141], v[138:139], v[148:149]
	v_pk_add_f32 v[138:139], v[138:139], v[148:149] neg_lo:[0,1] neg_hi:[0,1]
	v_pk_fma_f32 v[148:149], v[22:23], v[116:117], v[146:147] op_sel:[0,0,1] op_sel_hi:[1,1,0] neg_lo:[0,0,1]
	v_pk_mul_f32 v[146:147], v[38:39], v[114:115]
	v_pk_add_f32 v[116:117], v[148:149], v[142:143]
	v_pk_add_f32 v[142:143], v[142:143], v[148:149] neg_lo:[0,1] neg_hi:[0,1]
	v_pk_fma_f32 v[148:149], v[36:37], v[114:115], v[146:147] op_sel:[0,0,1] op_sel_hi:[1,1,0] neg_hi:[0,0,1]
	v_pk_mul_f32 v[146:147], v[30:31], v[124:125]
	v_pk_add_f32 v[114:115], v[148:149], v[144:145]
	v_pk_add_f32 v[144:145], v[144:145], v[148:149] neg_lo:[0,1] neg_hi:[0,1]
	v_pk_fma_f32 v[148:149], v[22:23], v[124:125], v[146:147] op_sel:[0,0,1] op_sel_hi:[1,1,0] neg_lo:[0,0,1]
	v_pk_mul_f32 v[146:147], v[38:39], v[122:123]
	v_pk_add_f32 v[124:125], v[120:121], v[148:149]
	v_pk_add_f32 v[120:121], v[120:121], v[148:149] neg_lo:[0,1] neg_hi:[0,1]
	v_pk_fma_f32 v[148:149], v[36:37], v[122:123], v[146:147] op_sel:[0,0,1] op_sel_hi:[1,1,0] neg_hi:[0,0,1]
	v_pk_mul_f32 v[146:147], v[30:31], v[132:133]
	v_pk_add_f32 v[122:123], v[118:119], v[148:149]
	v_pk_add_f32 v[118:119], v[118:119], v[148:149] neg_lo:[0,1] neg_hi:[0,1]
	v_pk_fma_f32 v[148:149], v[22:23], v[132:133], v[146:147] op_sel:[0,0,1] op_sel_hi:[1,1,0] neg_lo:[0,0,1]
	v_pk_mul_f32 v[146:147], v[38:39], v[130:131]
	v_pk_add_f32 v[132:133], v[128:129], v[148:149]
	v_pk_add_f32 v[128:129], v[128:129], v[148:149] neg_lo:[0,1] neg_hi:[0,1]
	v_pk_fma_f32 v[148:149], v[36:37], v[130:131], v[146:147] op_sel:[0,0,1] op_sel_hi:[1,1,0] neg_hi:[0,0,1]
	v_pk_mul_f32 v[146:147], v[30:31], v[140:141]
	v_pk_add_f32 v[130:131], v[126:127], v[148:149]
	v_pk_add_f32 v[126:127], v[126:127], v[148:149] neg_lo:[0,1] neg_hi:[0,1]
	v_pk_fma_f32 v[148:149], v[22:23], v[140:141], v[146:147] op_sel:[0,0,1] op_sel_hi:[1,1,0] neg_lo:[0,0,1]
	v_pk_mul_f32 v[146:147], v[38:39], v[138:139]
	v_pk_add_f32 v[140:141], v[136:137], v[148:149]
	v_pk_add_f32 v[136:137], v[136:137], v[148:149] neg_lo:[0,1] neg_hi:[0,1]
	v_pk_fma_f32 v[148:149], v[36:37], v[138:139], v[146:147] op_sel:[0,0,1] op_sel_hi:[1,1,0] neg_hi:[0,0,1]
	v_pk_mul_f32 v[146:147], v[34:35], v[124:125]
	v_pk_add_f32 v[138:139], v[134:135], v[148:149]
	v_pk_add_f32 v[134:135], v[134:135], v[148:149] neg_lo:[0,1] neg_hi:[0,1]
	v_pk_fma_f32 v[148:149], v[32:33], v[124:125], v[146:147] op_sel:[0,0,1] op_sel_hi:[1,1,0] neg_lo:[0,0,1]
	v_pk_mul_f32 v[146:147], v[46:47], v[122:123]
	v_pk_add_f32 v[124:125], v[116:117], v[148:149]
	v_pk_add_f32 v[116:117], v[116:117], v[148:149] neg_lo:[0,1] neg_hi:[0,1]
	v_pk_fma_f32 v[148:149], v[44:45], v[122:123], v[146:147] op_sel:[0,0,1] op_sel_hi:[1,1,0] neg_hi:[0,0,1]
	v_pk_mul_f32 v[146:147], v[50:51], v[120:121]
	v_pk_add_f32 v[122:123], v[114:115], v[148:149]
	v_pk_add_f32 v[114:115], v[114:115], v[148:149] neg_lo:[0,1] neg_hi:[0,1]
	v_pk_fma_f32 v[148:149], v[48:49], v[120:121], v[146:147] op_sel:[0,0,1] op_sel_hi:[1,1,0] neg_hi:[0,0,1]
	v_pk_mul_f32 v[146:147], v[40:41], v[118:119]
	v_pk_add_f32 v[120:121], v[142:143], v[148:149]
	v_pk_add_f32 v[142:143], v[142:143], v[148:149] neg_lo:[0,1] neg_hi:[0,1]
	v_pk_fma_f32 v[148:149], v[42:43], v[118:119], v[146:147] op_sel:[0,0,1] op_sel_hi:[1,1,0] neg_hi:[0,0,1]
	v_pk_mul_f32 v[146:147], v[34:35], v[140:141]
	v_pk_add_f32 v[118:119], v[144:145], v[148:149]
	v_pk_add_f32 v[144:145], v[144:145], v[148:149] neg_lo:[0,1] neg_hi:[0,1]
	v_pk_fma_f32 v[148:149], v[32:33], v[140:141], v[146:147] op_sel:[0,0,1] op_sel_hi:[1,1,0] neg_lo:[0,0,1]
	v_pk_mul_f32 v[146:147], v[46:47], v[138:139]
	v_pk_add_f32 v[140:141], v[132:133], v[148:149]
	v_pk_add_f32 v[132:133], v[132:133], v[148:149] neg_lo:[0,1] neg_hi:[0,1]
	v_pk_fma_f32 v[148:149], v[44:45], v[138:139], v[146:147] op_sel:[0,0,1] op_sel_hi:[1,1,0] neg_hi:[0,0,1]
	v_pk_mul_f32 v[146:147], v[50:51], v[136:137]
	v_pk_add_f32 v[138:139], v[130:131], v[148:149]
	v_pk_add_f32 v[130:131], v[130:131], v[148:149] neg_lo:[0,1] neg_hi:[0,1]
	v_pk_fma_f32 v[148:149], v[48:49], v[136:137], v[146:147] op_sel:[0,0,1] op_sel_hi:[1,1,0] neg_hi:[0,0,1]
	v_pk_mul_f32 v[146:147], v[40:41], v[134:135]
	v_pk_add_f32 v[136:137], v[128:129], v[148:149]
	v_pk_add_f32 v[128:129], v[128:129], v[148:149] neg_lo:[0,1] neg_hi:[0,1]
	v_pk_fma_f32 v[148:149], v[42:43], v[134:135], v[146:147] op_sel:[0,0,1] op_sel_hi:[1,1,0] neg_hi:[0,0,1]
	v_pk_mul_f32 v[146:147], v[54:55], v[140:141] op_sel:[0,1] op_sel_hi:[1,0]
	v_pk_add_f32 v[134:135], v[126:127], v[148:149]
	v_pk_add_f32 v[126:127], v[126:127], v[148:149] neg_lo:[0,1] neg_hi:[0,1]
	v_pk_fma_f32 v[148:149], v[52:53], v[140:141], v[146:147] neg_lo:[0,0,1]
	v_pk_mul_f32 v[146:147], v[64:65], v[138:139] op_sel:[0,1] op_sel_hi:[1,0]
	v_pk_add_f32 v[140:141], v[124:125], v[148:149]
	v_pk_add_f32 v[124:125], v[124:125], v[148:149] neg_lo:[0,1] neg_hi:[0,1]
	v_pk_fma_f32 v[148:149], v[60:61], v[138:139], v[146:147] neg_hi:[0,0,1]
	v_pk_mul_f32 v[146:147], v[72:73], v[136:137] op_sel:[0,1] op_sel_hi:[1,0]
	v_pk_add_f32 v[138:139], v[122:123], v[148:149]
	v_pk_add_f32 v[122:123], v[122:123], v[148:149] neg_lo:[0,1] neg_hi:[0,1]
	v_pk_fma_f32 v[148:149], v[70:71], v[136:137], v[146:147] neg_hi:[0,0,1]
	v_pk_mul_f32 v[146:147], v[76:77], v[134:135] op_sel:[0,1] op_sel_hi:[1,0]
	v_pk_add_f32 v[136:137], v[120:121], v[148:149]
	v_pk_add_f32 v[120:121], v[120:121], v[148:149] neg_lo:[0,1] neg_hi:[0,1]
	v_pk_fma_f32 v[148:149], v[62:63], v[134:135], v[146:147] neg_hi:[0,0,1]
	v_pk_mul_f32 v[146:147], v[80:81], v[132:133] op_sel:[0,1] op_sel_hi:[1,0]
	v_pk_add_f32 v[134:135], v[118:119], v[148:149]
	v_pk_add_f32 v[118:119], v[118:119], v[148:149] neg_lo:[0,1] neg_hi:[0,1]
	v_pk_fma_f32 v[148:149], v[78:79], v[132:133], v[146:147] neg_hi:[0,0,1]
	v_pk_mul_f32 v[146:147], v[56:57], v[130:131] op_sel:[0,1] op_sel_hi:[1,0]
	v_pk_add_f32 v[132:133], v[116:117], v[148:149]
	v_pk_add_f32 v[116:117], v[116:117], v[148:149] neg_lo:[0,1] neg_hi:[0,1]
	v_pk_fma_f32 v[148:149], v[74:75], v[130:131], v[146:147] neg_hi:[0,0,1]
	v_pk_mul_f32 v[146:147], v[66:67], v[128:129] op_sel:[0,1] op_sel_hi:[1,0]
	v_pk_add_f32 v[130:131], v[114:115], v[148:149]
	v_pk_add_f32 v[114:115], v[114:115], v[148:149] neg_lo:[0,1] neg_hi:[0,1]
	v_pk_fma_f32 v[148:149], v[68:69], v[128:129], v[146:147] neg_hi:[0,0,1]
	v_pk_mul_f32 v[146:147], v[82:83], v[126:127] op_sel:[0,1] op_sel_hi:[1,0]
	v_pk_add_f32 v[128:129], v[142:143], v[148:149]
	v_pk_add_f32 v[142:143], v[142:143], v[148:149] neg_lo:[0,1] neg_hi:[0,1]
	v_pk_fma_f32 v[148:149], v[58:59], v[126:127], v[146:147] neg_hi:[0,0,1]
	s_nop 0
	v_pk_add_f32 v[126:127], v[144:145], v[148:149]
	v_pk_add_f32 v[144:145], v[144:145], v[148:149] neg_lo:[0,1] neg_hi:[0,1]
	ds_write_b64 v150, v[140:141]
	ds_write_b64 v151, v[138:139] offset:512
	ds_write_b64 v152, v[136:137] offset:1024
	ds_write_b64 v153, v[134:135] offset:1536
	ds_write_b64 v154, v[132:133] offset:2048
	ds_write_b64 v155, v[130:131] offset:2560
	ds_write_b64 v156, v[128:129] offset:3072
	ds_write_b64 v157, v[126:127] offset:3584
	ds_write_b64 v158, v[124:125] offset:4096
	ds_write_b64 v159, v[122:123] offset:4608
	ds_write_b64 v160, v[120:121] offset:5120
	ds_write_b64 v161, v[118:119] offset:5632
	ds_write_b64 v162, v[116:117] offset:6144
	ds_write_b64 v163, v[114:115] offset:6656
	ds_write_b64 v164, v[142:143] offset:7168
	ds_write_b64 v165, v[144:145] offset:7680
	s_andn2_b64 exec, exec, s[12:13]
	s_cbranch_execnz .LBB0_699

.LBB0_702:
	v_and_b32_e32 v74, 0x3ff, v25
	v_lshlrev_b32_e32 v52, 3, v74
	v_and_or_b32 v53, v0, s38, v74
	v_cvt_f32_u32_e32 v52, v52
	v_ashrrev_i32_e32 v2, 5, v53
	v_lshl_add_u32 v55, v53, 3, 0
	v_or_b32_e32 v36, 0x2000, v53
	v_or_b32_e32 v38, 0x2400, v53
	v_or_b32_e32 v40, 0x2800, v53
	v_or_b32_e32 v42, 0x2c00, v53
	v_or_b32_e32 v44, 0x3000, v53
	v_or_b32_e32 v46, 0x3400, v53
	v_or_b32_e32 v48, 0x3800, v53
	v_or_b32_e32 v50, 0x3c00, v53
	v_lshl_add_u32 v66, v2, 3, v55
	v_or_b32_e32 v2, 0x800, v53
	s_waitcnt vmcnt(0)
	v_or_b32_e32 v20, 0xc00, v53
	v_or_b32_e32 v22, 0x1000, v53
	v_or_b32_e32 v30, 0x1400, v53
	v_or_b32_e32 v32, 0x1800, v53
	v_or_b32_e32 v34, 0x1c00, v53
	v_ashrrev_i32_e32 v37, 5, v36
	v_ashrrev_i32_e32 v39, 5, v38
	v_ashrrev_i32_e32 v41, 5, v40
	v_ashrrev_i32_e32 v43, 5, v42
	v_ashrrev_i32_e32 v45, 5, v44
	v_ashrrev_i32_e32 v47, 5, v46
	v_ashrrev_i32_e32 v49, 5, v48
	v_ashrrev_i32_e32 v51, 5, v50
	v_or_b32_e32 v53, 0x400, v53
	v_ashrrev_i32_e32 v2, 5, v2
	v_ashrrev_i32_e32 v20, 5, v20
	v_ashrrev_i32_e32 v22, 5, v22
	v_ashrrev_i32_e32 v30, 5, v30
	v_ashrrev_i32_e32 v32, 5, v32
	v_ashrrev_i32_e32 v34, 5, v34
	v_lshlrev_b32_e32 v36, 3, v36
	v_lshlrev_b32_e32 v37, 3, v37
	v_lshlrev_b32_e32 v38, 3, v38
	v_lshlrev_b32_e32 v39, 3, v39
	v_lshlrev_b32_e32 v40, 3, v40
	v_lshlrev_b32_e32 v41, 3, v41
	v_lshlrev_b32_e32 v42, 3, v42
	v_lshlrev_b32_e32 v43, 3, v43
	v_lshlrev_b32_e32 v44, 3, v44
	v_lshlrev_b32_e32 v45, 3, v45
	v_lshlrev_b32_e32 v46, 3, v46
	v_lshlrev_b32_e32 v47, 3, v47
	v_lshlrev_b32_e32 v48, 3, v48
	v_lshlrev_b32_e32 v49, 3, v49
	v_lshlrev_b32_e32 v50, 3, v50
	v_lshlrev_b32_e32 v51, 3, v51
	v_ashrrev_i32_e32 v53, 5, v53
	v_lshl_add_u32 v67, v2, 3, v55
	v_lshl_add_u32 v68, v20, 3, v55
	v_lshl_add_u32 v69, v22, 3, v55
	v_lshl_add_u32 v70, v30, 3, v55
	v_lshl_add_u32 v71, v32, 3, v55
	v_lshl_add_u32 v72, v34, 3, v55
	v_add3_u32 v36, 0, v36, v37
	v_add3_u32 v38, 0, v38, v39
	v_add3_u32 v40, 0, v40, v41
	v_add3_u32 v42, 0, v42, v43
	v_add3_u32 v44, 0, v44, v45
	v_add3_u32 v46, 0, v46, v47
	v_add3_u32 v48, 0, v48, v49
	v_add3_u32 v50, 0, v50, v51
	v_mul_f32_e32 v54, 0x38800000, v52
	v_lshl_add_u32 v73, v53, 3, v55
	ds_read_b64 v[2:3], v67 offset:16384
	ds_read_b64 v[20:21], v68 offset:24576
	ds_read_b64 v[22:23], v69 offset:32768
	ds_read_b64 v[30:31], v70 offset:40960
	ds_read_b64 v[32:33], v71 offset:49152
	ds_read_b64 v[34:35], v72 offset:57344
	ds_read_b64 v[36:37], v36
	ds_read_b64 v[38:39], v38
	ds_read_b64 v[40:41], v40
	ds_read_b64 v[42:43], v42
	ds_read_b64 v[44:45], v44
	ds_read_b64 v[46:47], v46
	ds_read_b64 v[48:49], v48
	ds_read_b64 v[50:51], v50
	v_cos_f32_e32 v52, v54
	v_sin_f32_e32 v54, v54
	ds_read_b64 v[56:57], v73 offset:8192
	ds_read_b64 v[58:59], v66
	s_mov_b32 s89, s94
	s_mov_b32 s27, s14
	s_mov_b32 s81, s15
	s_waitcnt lgkmcnt(1)
	v_pk_mul_f32 v[60:61], v[54:55], v[56:57] op_sel_hi:[0,1]
	v_pk_fma_f32 v[62:63], v[52:53], v[56:57], v[60:61] op_sel:[0,0,1] op_sel_hi:[0,1,0] neg_lo:[0,0,1]
	v_pk_mul_f32 v[60:61], v[20:21], v[54:55] op_sel_hi:[1,0]
	s_waitcnt lgkmcnt(0)
	v_pk_add_f32 v[56:57], v[58:59], v[62:63]
	v_pk_add_f32 v[58:59], v[58:59], v[62:63] neg_lo:[0,1] neg_hi:[0,1]
	v_pk_fma_f32 v[62:63], v[20:21], v[52:53], v[60:61] op_sel:[0,0,1] op_sel_hi:[1,0,0] neg_lo:[0,0,1]
	v_pk_mul_f32 v[60:61], v[54:55], v[30:31] op_sel_hi:[0,1]
	v_pk_add_f32 v[20:21], v[2:3], v[62:63]
	v_pk_add_f32 v[2:3], v[2:3], v[62:63] neg_lo:[0,1] neg_hi:[0,1]
	v_pk_fma_f32 v[62:63], v[30:31], v[52:53], v[60:61] op_sel:[0,0,1] op_sel_hi:[1,0,0] neg_lo:[0,0,1]
	v_pk_mul_f32 v[60:61], v[54:55], v[34:35] op_sel_hi:[0,1]
	v_pk_add_f32 v[30:31], v[22:23], v[62:63]
	v_pk_add_f32 v[22:23], v[22:23], v[62:63] neg_lo:[0,1] neg_hi:[0,1]
	v_pk_fma_f32 v[62:63], v[52:53], v[34:35], v[60:61] op_sel:[0,0,1] op_sel_hi:[0,1,0] neg_lo:[0,0,1]
	v_pk_add_f32 v[60:61], v[32:33], v[62:63]
	v_pk_add_f32 v[62:63], v[32:33], v[62:63] neg_lo:[0,1] neg_hi:[0,1]
	v_pk_mul_f32 v[32:33], v[54:55], v[38:39] op_sel_hi:[0,1]
	v_pk_fma_f32 v[34:35], v[52:53], v[38:39], v[32:33] op_sel:[0,0,1] op_sel_hi:[0,1,0] neg_lo:[0,0,1]
	v_pk_mul_f32 v[32:33], v[54:55], v[42:43] op_sel_hi:[0,1]
	v_pk_add_f32 v[38:39], v[36:37], v[34:35]
	v_pk_add_f32 v[64:65], v[36:37], v[34:35] neg_lo:[0,1] neg_hi:[0,1]
	v_pk_fma_f32 v[34:35], v[52:53], v[42:43], v[32:33] op_sel:[0,0,1] op_sel_hi:[0,1,0] neg_lo:[0,0,1]
	v_pk_mul_f32 v[32:33], v[54:55], v[46:47] op_sel_hi:[0,1]
	v_pk_add_f32 v[36:37], v[40:41], v[34:35]
	v_pk_add_f32 v[40:41], v[40:41], v[34:35] neg_lo:[0,1] neg_hi:[0,1]
	v_pk_fma_f32 v[34:35], v[52:53], v[46:47], v[32:33] op_sel:[0,0,1] op_sel_hi:[0,1,0] neg_lo:[0,0,1]
	v_pk_mul_f32 v[32:33], v[54:55], v[50:51] op_sel_hi:[0,1]
	v_pk_add_f32 v[46:47], v[44:45], v[34:35]
	v_pk_add_f32 v[76:77], v[44:45], v[34:35] neg_lo:[0,1] neg_hi:[0,1]
	v_pk_fma_f32 v[34:35], v[52:53], v[50:51], v[32:33] op_sel:[0,0,1] op_sel_hi:[1,1,0] neg_lo:[0,0,1] neg_hi:[0,0,1]
	v_pk_fma_f32 v[32:33], v[52:53], v[50:51], v[32:33] op_sel:[0,0,1] op_sel_hi:[0,1,0]
	v_lshlrev_b32_e32 v32, 2, v74
	v_cvt_f32_u32_e32 v32, v32
	v_mov_b32_e32 v35, v33
	v_pk_add_f32 v[44:45], v[48:49], v[34:35]
	v_pk_add_f32 v[54:55], v[48:49], v[34:35] neg_lo:[0,1] neg_hi:[0,1]
	v_mul_f32_e32 v32, 0x38800000, v32
	v_sin_f32_e32 v78, v32
	v_cos_f32_e32 v52, v32
	v_cmp_lt_i32_e32 vcc, s35, v25
	v_add_u32_e32 v0, 0x2000, v0
	v_pk_mul_f32 v[32:33], v[78:79], v[20:21] op_sel_hi:[0,1]
	v_pk_fma_f32 v[34:35], v[52:53], v[20:21], v[32:33] op_sel:[0,0,1] op_sel_hi:[0,1,0] neg_lo:[0,0,1]
	v_fma_f32 v82, v78, s39, -v52
	v_pk_add_f32 v[80:81], v[34:35], v[56:57]
	v_pk_add_f32 v[34:35], v[56:57], v[34:35] neg_lo:[0,1] neg_hi:[0,1]
	v_fma_f32 v56, v52, 0, -v78
	v_pk_mul_f32 v[20:21], v[82:83], v[2:3] op_sel_hi:[0,1]
	v_pk_fma_f32 v[42:43], v[56:57], v[2:3], v[20:21] op_sel:[0,0,1] op_sel_hi:[0,1,0] neg_hi:[0,0,1]
	v_pk_mul_f32 v[2:3], v[78:79], v[60:61] op_sel_hi:[0,1]
	v_pk_add_f32 v[32:33], v[42:43], v[58:59]
	v_pk_add_f32 v[20:21], v[58:59], v[42:43] neg_lo:[0,1] neg_hi:[0,1]
	v_pk_fma_f32 v[42:43], v[52:53], v[60:61], v[2:3] op_sel:[0,0,1] op_sel_hi:[0,1,0] neg_lo:[0,0,1]
	v_pk_add_f32 v[2:3], v[30:31], v[42:43]
	v_pk_add_f32 v[50:51], v[30:31], v[42:43] neg_lo:[0,1] neg_hi:[0,1]
	v_pk_mul_f32 v[30:31], v[82:83], v[62:63] op_sel_hi:[0,1]
	v_pk_fma_f32 v[42:43], v[56:57], v[62:63], v[30:31] op_sel:[0,0,1] op_sel_hi:[0,1,0] neg_hi:[0,0,1]
	v_pk_add_f32 v[48:49], v[22:23], v[42:43]
	v_pk_add_f32 v[42:43], v[22:23], v[42:43] neg_lo:[0,1] neg_hi:[0,1]
	v_pk_mul_f32 v[22:23], v[78:79], v[36:37] op_sel_hi:[0,1]
	v_pk_fma_f32 v[30:31], v[52:53], v[36:37], v[22:23] op_sel:[0,0,1] op_sel_hi:[0,1,0] neg_lo:[0,0,1]
	v_pk_add_f32 v[36:37], v[38:39], v[30:31]
	v_pk_add_f32 v[22:23], v[38:39], v[30:31] neg_lo:[0,1] neg_hi:[0,1]
	v_pk_mul_f32 v[30:31], v[82:83], v[40:41] op_sel_hi:[0,1]
	v_pk_fma_f32 v[58:59], v[56:57], v[40:41], v[30:31] op_sel:[0,0,1] op_sel_hi:[0,1,0] neg_hi:[0,0,1]
	v_pk_mul_f32 v[40:41], v[78:79], v[44:45] op_sel_hi:[0,1]
	v_pk_add_f32 v[38:39], v[64:65], v[58:59]
	v_pk_add_f32 v[30:31], v[64:65], v[58:59] neg_lo:[0,1] neg_hi:[0,1]
	v_pk_fma_f32 v[58:59], v[52:53], v[44:45], v[40:41] op_sel:[0,0,1] op_sel_hi:[0,1,0] neg_lo:[0,0,1]
	v_pk_mul_f32 v[40:41], v[82:83], v[54:55] op_sel_hi:[0,1]
	v_pk_add_f32 v[52:53], v[46:47], v[58:59]
	v_pk_add_f32 v[44:45], v[46:47], v[58:59] neg_lo:[0,1] neg_hi:[0,1]
	v_pk_fma_f32 v[46:47], v[56:57], v[54:55], v[40:41] op_sel:[0,0,1] op_sel_hi:[1,1,0]
	v_pk_fma_f32 v[40:41], v[56:57], v[54:55], v[40:41] op_sel:[0,0,1] op_sel_hi:[0,1,0] neg_lo:[0,0,1] neg_hi:[0,0,1]
	v_lshlrev_b32_e32 v40, 1, v74
	v_cvt_f32_u32_e32 v40, v40
	v_mov_b32_e32 v47, v41
	v_pk_add_f32 v[54:55], v[76:77], v[46:47]
	v_pk_add_f32 v[46:47], v[76:77], v[46:47] neg_lo:[0,1] neg_hi:[0,1]
	v_mul_f32_e32 v40, 0x38800000, v40
	v_sin_f32_e32 v58, v40
	v_cos_f32_e32 v56, v40
	s_or_b64 s[12:13], vcc, s[12:13]
	v_pk_mul_f32 v[40:41], v[58:59], v[2:3] op_sel_hi:[0,1]
	v_pk_fma_f32 v[60:61], v[56:57], v[2:3], v[40:41] op_sel:[0,0,1] op_sel_hi:[0,1,0] neg_lo:[0,0,1]
	v_pk_add_f32 v[40:41], v[80:81], v[60:61]
	v_pk_add_f32 v[2:3], v[80:81], v[60:61] neg_lo:[0,1] neg_hi:[0,1]
	v_fma_f32 v80, v58, s39, -v56
	v_fma_f32 v78, v56, 0, -v58
	v_pk_mul_f32 v[60:61], v[80:81], v[50:51] op_sel_hi:[0,1]
	v_mov_b32_e32 v59, v56
	v_pk_fma_f32 v[82:83], v[78:79], v[50:51], v[60:61] op_sel:[0,0,1] op_sel_hi:[0,1,0] neg_hi:[0,0,1]
	v_pk_mul_f32 v[62:63], v[58:59], s[88:89]
	v_mov_b32_e32 v57, v58
	v_pk_add_f32 v[64:65], v[62:63], v[62:63] op_sel:[0,1] op_sel_hi:[0,1] neg_lo:[0,1] neg_hi:[0,1]
	v_pk_add_f32 v[60:61], v[34:35], v[82:83]
	v_pk_add_f32 v[50:51], v[34:35], v[82:83] neg_lo:[0,1] neg_hi:[0,1]
	v_pk_mul_f32 v[82:83], v[56:57], s[88:89]
	v_pk_mul_f32 v[76:77], v[64:65], v[48:49]
	v_sub_f32_e32 v114, v63, v83
	v_pk_fma_f32 v[116:117], v[114:115], v[48:49], v[76:77] op_sel:[0,0,1] op_sel_hi:[0,1,0] neg_hi:[0,0,1]
	v_pk_add_f32 v[76:77], v[82:83], v[82:83] op_sel:[0,1] op_sel_hi:[0,1] neg_lo:[0,1] neg_hi:[0,1]
	v_sub_f32_e32 v82, v83, v63
	v_pk_mul_f32 v[48:49], v[82:83], v[42:43] op_sel_hi:[0,1]
	v_pk_add_f32 v[34:35], v[32:33], v[116:117]
	v_pk_add_f32 v[32:33], v[32:33], v[116:117] neg_lo:[0,1] neg_hi:[0,1]
	v_pk_fma_f32 v[116:117], v[76:77], v[42:43], v[48:49] op_sel:[0,0,1] op_sel_hi:[1,1,0] neg_hi:[0,0,1]
	v_pk_mul_f32 v[42:43], v[58:59], v[52:53] op_sel_hi:[0,1]
	v_pk_fma_f32 v[48:49], v[56:57], v[52:53], v[42:43] op_sel:[0,0,1] op_sel_hi:[0,1,0] neg_lo:[0,0,1]
	v_pk_add_f32 v[58:59], v[36:37], v[48:49]
	v_pk_add_f32 v[52:53], v[36:37], v[48:49] neg_lo:[0,1] neg_hi:[0,1]
	v_pk_mul_f32 v[36:37], v[64:65], v[54:55]
	v_pk_add_f32 v[62:63], v[20:21], v[116:117]
	v_pk_fma_f32 v[48:49], v[114:115], v[54:55], v[36:37] op_sel:[0,0,1] op_sel_hi:[0,1,0] neg_hi:[0,0,1]
	v_pk_add_f32 v[42:43], v[38:39], v[48:49]
	v_pk_add_f32 v[36:37], v[38:39], v[48:49] neg_lo:[0,1] neg_hi:[0,1]
	v_pk_mul_f32 v[38:39], v[80:81], v[44:45] op_sel_hi:[0,1]
	v_pk_fma_f32 v[48:49], v[78:79], v[44:45], v[38:39] op_sel:[0,0,1] op_sel_hi:[0,1,0] neg_hi:[0,0,1]
	v_pk_add_f32 v[54:55], v[22:23], v[48:49]
	v_pk_add_f32 v[48:49], v[22:23], v[48:49] neg_lo:[0,1] neg_hi:[0,1]
	v_pk_mul_f32 v[22:23], v[82:83], v[46:47] op_sel_hi:[0,1]
	v_pk_fma_f32 v[38:39], v[76:77], v[46:47], v[22:23] op_sel:[0,0,1] op_sel_hi:[1,1,0] neg_hi:[0,0,1]
	v_pk_add_f32 v[20:21], v[20:21], v[116:117] neg_lo:[0,1] neg_hi:[0,1]
	v_pk_add_f32 v[64:65], v[30:31], v[38:39]
	v_pk_add_f32 v[22:23], v[30:31], v[38:39] neg_lo:[0,1] neg_hi:[0,1]
	v_cvt_f32_u32_e32 v30, v74
	v_mul_f32_e32 v30, 0x38800000, v30
	v_sin_f32_e32 v56, v30
	v_cos_f32_e32 v44, v30
	v_pk_mul_f32 v[30:31], v[56:57], v[58:59] op_sel:[0,1] op_sel_hi:[0,0]
	v_pk_fma_f32 v[38:39], v[44:45], v[58:59], v[30:31] op_sel_hi:[0,1,1] neg_lo:[0,0,1]
	v_mov_b32_e32 v57, v44
	v_pk_mul_f32 v[46:47], v[56:57], s[88:89]
	v_pk_add_f32 v[30:31], v[40:41], v[38:39]
	v_pk_add_f32 v[38:39], v[46:47], v[46:47] op_sel:[0,1] op_sel_hi:[0,1] neg_lo:[0,1] neg_hi:[0,1]
	v_pk_mul_f32 v[74:75], v[56:57], s[26:27]
	v_pk_mul_f32 v[58:59], v[38:39], v[54:55] op_sel:[0,1] op_sel_hi:[1,0]
	v_pk_mul_f32 v[38:39], v[56:57], s[14:15]
	v_pk_add_f32 v[78:79], v[74:75], v[74:75] op_sel:[0,1] op_sel_hi:[0,1] neg_lo:[0,1] neg_hi:[0,1]
	v_pk_add_f32 v[76:77], v[38:39], v[38:39] op_sel:[1,0] op_sel_hi:[1,0] neg_lo:[0,1] neg_hi:[0,1]
	v_pk_mul_f32 v[78:79], v[78:79], v[64:65] op_sel:[0,1] op_sel_hi:[1,0]
	v_fma_f32 v46, v44, 0, -v56
	v_pk_fma_f32 v[80:81], v[76:77], v[64:65], v[78:79]
	v_pk_fma_f32 v[64:65], v[76:77], v[64:65], v[78:79] neg_lo:[0,0,1] neg_hi:[0,0,1]
	v_mov_b32_e32 v45, v56
	v_fma_f32 v64, v56, s39, -v44
	v_mov_b32_e32 v81, v65
	v_pk_mul_f32 v[64:65], v[64:65], v[52:53] op_sel:[0,1] op_sel_hi:[0,0]
	v_pk_fma_f32 v[76:77], v[46:47], v[52:53], v[64:65] op_sel_hi:[0,1,1] neg_hi:[0,0,1]
	v_pk_mul_f32 v[52:53], v[44:45], s[88:89]
	v_fma_f32 v40, v56, s80, -v39
	v_sub_f32_e32 v56, v47, v53
	v_pk_fma_f32 v[64:65], v[56:57], v[54:55], v[58:59] op_sel_hi:[0,1,1]
	v_pk_fma_f32 v[54:55], v[56:57], v[54:55], v[58:59] op_sel_hi:[0,1,1] neg_lo:[0,0,1] neg_hi:[0,0,1]
	v_pk_add_f32 v[56:57], v[52:53], v[52:53] op_sel:[0,1] op_sel_hi:[0,1] neg_lo:[0,1] neg_hi:[0,1]
	v_sub_f32_e32 v52, v53, v47
	v_pk_mul_f32 v[52:53], v[52:53], v[48:49] op_sel:[0,1] op_sel_hi:[0,0]
	v_pk_fma_f32 v[58:59], v[56:57], v[48:49], v[52:53] neg_hi:[0,0,1]
	v_fma_f32 v46, v44, s26, -v38
	v_pk_mul_f32 v[44:45], v[44:45], s[80:81]
	v_pk_mul_f32 v[40:41], v[40:41], v[42:43] op_sel:[0,1] op_sel_hi:[0,0]
	v_pk_add_f32 v[48:49], v[50:51], v[58:59]
	v_sub_f32_e32 v50, v75, v45
	v_pk_fma_f32 v[52:53], v[50:51], v[42:43], v[40:41] op_sel_hi:[0,1,1]
	v_pk_fma_f32 v[40:41], v[50:51], v[42:43], v[40:41] op_sel_hi:[0,1,1] neg_lo:[0,0,1] neg_hi:[0,0,1]
	v_sub_f32_e32 v40, v45, v75
	v_mov_b32_e32 v53, v41
	v_pk_mul_f32 v[40:41], v[40:41], v[36:37] op_sel:[0,1] op_sel_hi:[0,0]
	v_pk_fma_f32 v[42:43], v[46:47], v[36:37], v[40:41] op_sel_hi:[0,1,1] neg_hi:[0,0,1]
	v_pk_add_f32 v[38:39], v[38:39], v[38:39] op_sel:[0,1] op_sel_hi:[0,1] neg_lo:[0,1] neg_hi:[0,1]
	v_pk_add_f32 v[36:37], v[44:45], v[44:45] op_sel:[0,1] op_sel_hi:[0,1] neg_lo:[0,1] neg_hi:[0,1]
	v_pk_mul_f32 v[38:39], v[38:39], v[22:23] op_sel:[0,1] op_sel_hi:[1,0]
	v_pk_add_f32 v[2:3], v[2:3], v[76:77]
	v_pk_fma_f32 v[40:41], v[36:37], v[22:23], v[38:39] neg_hi:[0,0,1]
	v_mov_b32_e32 v65, v55
	v_pk_add_f32 v[62:63], v[62:63], v[80:81]
	v_pk_add_f32 v[54:55], v[60:61], v[64:65]
	v_pk_add_f32 v[34:35], v[34:35], v[52:53]
	v_pk_add_f32 v[32:33], v[32:33], v[42:43]
	v_pk_add_f32 v[20:21], v[20:21], v[40:41]
	ds_write_b64 v66, v[30:31]
	ds_write_b64 v73, v[34:35] offset:8192
	ds_write_b64 v67, v[54:55] offset:16384
	ds_write_b64 v68, v[62:63] offset:24576
	ds_write_b64 v69, v[2:3] offset:32768
	ds_write_b64 v70, v[32:33] offset:40960
	ds_write_b64 v71, v[48:49] offset:49152
	ds_write_b64 v72, v[20:21] offset:57344
	v_add_u32_e32 v2, 0x200, v25
	v_mov_b32_e32 v25, v2
	s_andn2_b64 exec, exec, s[12:13]
	s_cbranch_execnz .LBB0_702
